# dense attention: global K/V loads issued two tiles ahead (two staging register sets), MFMA segments at raised priority, row-max folded into PV shadow
# speedup vs baseline: 1.0219x; 1.0219x over previous
; __device__ __forceinline__ int TID() { int t = threadIdx.x; asm volatile("" : "+v"(t)); return t; }
; __device__ __forceinline__ int v_rd_base(int lane) { return ((lane & 3) << 3) | (((lane >> 2) & 3) << 6) | (((lane >> 4) & 1) << 5) | (((lane >> 5) & 1) << 8); }
; #define SWAIT() do { if constexpr (SDEPTH == 2) asm volatile("s_waitcnt vmcnt(4)" ::: "memory"); else asm volatile("s_waitcnt vmcnt(0)" ::: "memory"); } while (0)
; #define ROW0(t) tile_row0<MODE>(u, (t))
; template <int MODE, int SDEPTH>
; __device__ __forceinline__ void attn_unit(const UnitP& u, char* lds) {
;   const int tid = TID(), wid = tid >> 6, lane = tid & 63, r32 = lane & 31, hi = lane >> 5;
;   bf16_t* V_lds = (bf16_t*)lds; bf16_t* K_lds = (bf16_t*)(lds + 2 * SHM_V);
;   float* ws = (float*)(lds + 2 * SHM_V + 2 * SHM_K) + wid * 64; float* li_l = ws; float* al_l = ws + 32;
;   const float* biasL = (const float*)(lds + BIAS_OFF);
;   const bf16_t* __restrict__ Kh = u.K; const bf16_t* __restrict__ Vh = u.V; const int LDK = u.ldk;
;   float m_reg = -1e30f, l_reg = 0; f32x16 o[4] = {}; bf16x8 qr[8];
;   const bf16_t* Qw = u.Q + (long)(wid * QBLK + r32) * u.ldq + hi * 8;
; #pragma unroll
;   for (int d0 = 0; d0 < 8; ++d0) qr[d0] = *reinterpret_cast<const bf16x8*>(Qw + d0 * 16);
;   const int vb0 = (int)(uintptr_t)V_lds + v_rd_base(lane);
;   struct { bf16x8 vs0, vs1, ks0, ks1; } sr_[SDEPTH];
;     ...
;   f32x16 pA0, pA1, pB0, pB1; float mnA, mnB, alA, alB; bf16x8 pa0, pa1, pa2, pa3; const int NT = u.NT;
;   constexpr int SE = 0, SO = SDEPTH - 1;
;   SLOAD(SE, ROW0(0)); asm volatile("s_waitcnt vmcnt(0)" ::: "memory"); SWRITE(0, SE); __syncthreads();
;   qkt(pA0, pA1, K_lds, qr, r32, hi); mask_tile<MODE>(pA0, pA1, u, 0, wid, r32, hi, biasL); partialSM(pA0, pA1, m_reg, mnA, alA);
;   SLOAD(SO, ROW0(1)); if constexpr (SDEPTH == 2) { if (2 < NT) SLOAD(SE, ROW0(2)); }
;   SWAIT(); SWRITE(1, SO); __syncthreads();
; __device__ __forceinline__ void attn_phase1(const Args& a, unsigned char* lds_g, int G) {
;     ...
;         const int h = un >> 5, qb = un & 31, kvh = h >> 2;
;         att::UnitP u; u.ldq = C_IN; u.ldk = C_IN; u.ldo = DM; u.sink_l2e = -INFINITY;
;         u.Q = P + (size_t)(256 * qb) * C_IN + h * 128; u.K = P + (16 + kvh) * 128; u.V = P + (20 + kvh) * 128; u.O = O + (size_t)(256 * qb) * DM + h * 128;
;         u.NT = MT / 64; u.base_row = 0; u.qb = qb;
.LBB0_528:
	s_andn2_b64 vcc, exec, s[8:9]
	s_mov_b64 s[8:9], -1
	s_cbranch_vccnz .LBB0_524
	s_lshl_b32 s2, s12, 8
	s_and_b32 s29, s2, 0x1f00
	s_and_b32 s13, s12, 0xffffff80
	s_mul_i32 s2, s29, 0x1800
	s_add_u32 s10, s19, s2
	s_addc_u32 s11, s20, 0
	s_lshl_b32 s2, s12, 2
	s_and_b32 s2, s2, 0xffffff80
	s_ashr_i32 s3, s2, 31
	s_lshl_b64 s[8:9], s[2:3], 1
	s_add_u32 s2, s10, s8
	s_addc_u32 s3, s11, s9
	s_add_i32 s10, s13, 0x800
	s_ashr_i32 s11, s10, 31
	s_lshl_b64 s[10:11], s[10:11], 1
	s_add_u32 s14, s19, s10
	s_addc_u32 s15, s20, s11
	s_add_i32 s12, s13, 0xa00
	s_ashr_i32 s13, s12, 31
	s_lshl_b64 s[12:13], s[12:13], 1
	v_mov_b32_e32 v48, v216
	s_add_u32 s16, s19, s12
	s_addc_u32 s17, s20, s13
	v_ashrrev_i32_e32 v195, 6, v48
	v_and_b32_e32 v193, 31, v48
	v_and_b32_e32 v0, 0x3fffffc0, v48
	s_add_i32 s34, 0, 0x10000
	v_lshlrev_b32_e32 v98, 5, v195
	v_bfe_u32 v194, v48, 5, 1
	v_lshl_add_u32 v99, v0, 2, s34
	v_or_b32_e32 v2, v98, v193
	v_mov_b64_e32 v[0:1], s[2:3]
	s_movk_i32 s36, 0x1800
	v_mad_i64_i32 v[0:1], s[2:3], v2, s36, v[0:1]
	v_lshlrev_b32_e32 v96, 4, v194
	v_and_b32_e32 v101, 63, v48
	v_lshl_add_u64 v[0:1], v[0:1], 0, v[96:97]
	v_lshlrev_b32_e32 v192, 4, v48
	global_load_dwordx4 v[130:133], v[0:1], off
	global_load_dwordx4 v[126:129], v[0:1], off offset:32
	global_load_dwordx4 v[122:125], v[0:1], off offset:64
	global_load_dwordx4 v[118:121], v[0:1], off offset:96
	global_load_dwordx4 v[114:117], v[0:1], off offset:128
	global_load_dwordx4 v[110:113], v[0:1], off offset:160
	global_load_dwordx4 v[106:109], v[0:1], off offset:192
	global_load_dwordx4 v[102:105], v[0:1], off offset:224
	v_lshlrev_b32_e32 v99, 8, v195
	v_add_u32_e32 v99, 0x22000, v99
	v_lshl_add_u32 v199, v193, 2, v99
	v_cmp_gt_u32_e64 s[40:41], 32, v101
	v_lshlrev_b32_e32 v0, 3, v101
	v_and_b32_e32 v1, 0xc0, v192
	v_lshlrev_b32_e32 v2, 1, v48
	v_and_or_b32 v1, v0, 24, v1
	v_and_b32_e32 v2, 32, v2
	v_and_b32_e32 v0, 0x100, v0
	v_or3_b32 v196, v1, v2, v0
	v_ashrrev_i32_e32 v50, 4, v48
	v_lshlrev_b32_e32 v16, 3, v48
	v_and_b32_e32 v51, 0x78, v16
	v_and_b32_e32 v3, 15, v48
	v_lshlrev_b32_e32 v3, 4, v3
	s_movk_i32 s2, 0x1800
	v_mad_u32_u24 v184, v50, s2, v3
	s_add_u32 s2, s16, 0x30000
	s_addc_u32 s3, s17, 0
	s_add_u32 s10, s14, 0x30000
	s_addc_u32 s11, s15, 0
	global_load_dwordx4 v[134:137], v184, s[16:17]
	global_load_dwordx4 v[138:141], v184, s[2:3]
	global_load_dwordx4 v[142:145], v184, s[14:15]
	global_load_dwordx4 v[146:149], v184, s[10:11]
	s_add_u32 s16, s16, 0x60000
	s_addc_u32 s17, s17, 0
	s_add_u32 s2, s2, 0x60000
	s_addc_u32 s3, s3, 0
	s_add_u32 s14, s14, 0x60000
	s_addc_u32 s15, s15, 0
	s_add_u32 s10, s10, 0x60000
	s_addc_u32 s11, s11, 0
	global_load_dwordx4 v[150:153], v184, s[16:17]
	global_load_dwordx4 v[154:157], v184, s[2:3]
	global_load_dwordx4 v[158:161], v184, s[14:15]
	global_load_dwordx4 v[162:165], v184, s[10:11]
	s_add_u32 s16, s16, 0x60000
	s_addc_u32 s17, s17, 0
	s_add_u32 s2, s2, 0x60000
	s_addc_u32 s3, s3, 0
	s_add_u32 s14, s14, 0x60000
	s_addc_u32 s15, s15, 0
	s_add_u32 s10, s10, 0x60000
	s_addc_u32 s11, s11, 0
	v_and_b32_e32 v18, 0xfffff0, v50
	v_lshlrev_b32_e32 v19, 1, v50
	v_and_or_b32 v18, v19, 8, v18
	v_lshrrev_b32_e32 v19, 1, v50
	v_lshrrev_b32_e32 v18, 1, v18
	v_bfe_u32 v16, v16, 5, 2
	v_and_b32_e32 v20, 3, v50
	v_or_b32_e32 v18, v18, v16
	v_and_or_b32 v19, v19, 4, v20
	v_lshlrev_b32_e32 v20, 1, v51
	v_lshlrev_b32_e32 v18, 9, v18
	v_lshlrev_b32_e32 v19, 6, v19
	v_and_b32_e32 v21, 48, v20
	v_or3_b32 v197, v18, v19, v21
	v_lshlrev_b32_e32 v4, 8, v50
	v_and_b32_e32 v5, 0xf0, v48
	v_bitop3_b32 v4, v20, v4, v5 bitop3:0xde
	v_add_u32_e32 v185, 0x10000, v4
	v_lshlrev_b32_e32 v60, 8, v193
	v_and_b32_e32 v61, 0xf0, v192
	v_bitop3_b32 v52, v96, v60, v61 bitop3:0xde
	v_add_u32_e32 v204, 0x10000, v52
	v_or_b32_e32 v52, 32, v96
	v_bitop3_b32 v52, v52, v60, v61 bitop3:0xde
	v_add_u32_e32 v205, 0x10000, v52
	v_or_b32_e32 v52, 64, v96
	v_bitop3_b32 v52, v52, v60, v61 bitop3:0xde
	v_add_u32_e32 v206, 0x10000, v52
	v_or_b32_e32 v52, 96, v96
	v_bitop3_b32 v52, v52, v60, v61 bitop3:0xde
	v_add_u32_e32 v207, 0x10000, v52
	v_or_b32_e32 v52, 128, v96
	v_bitop3_b32 v52, v52, v60, v61 bitop3:0xde
	v_add_u32_e32 v208, 0x10000, v52
	v_or_b32_e32 v52, 160, v96
	v_bitop3_b32 v52, v52, v60, v61 bitop3:0xde
	v_add_u32_e32 v209, 0x10000, v52
	v_or_b32_e32 v52, 192, v96
	v_bitop3_b32 v52, v52, v60, v61 bitop3:0xde
	v_add_u32_e32 v210, 0x10000, v52
	v_or_b32_e32 v52, 224, v96
	v_bitop3_b32 v52, v52, v60, v61 bitop3:0xde
	v_add_u32_e32 v211, 0x10000, v52
	v_mov_b32_e32 v174, v224
	v_mov_b32_e32 v175, 0
	s_mov_b32 s31, 0
	v_readfirstlane_b32 s36, v195
	s_waitcnt vmcnt(4)
	ds_write_b128 v197, v[134:137] offset:0
	ds_write_b128 v197, v[138:141] offset:8192
	ds_write_b128 v185, v[142:145] offset:0
	ds_write_b128 v185, v[146:149] offset:8192
	s_waitcnt vmcnt(0)
; #define SBAR() __builtin_amdgcn_sched_barrier(0)
; #define SWAIT() do { if constexpr (SDEPTH == 2) asm volatile("s_waitcnt vmcnt(4)" ::: "memory"); else asm volatile("s_waitcnt vmcnt(0)" ::: "memory"); } while (0)
; #define ROW0(t) tile_row0<MODE>(u, (t))
; __device__ __forceinline__ void partialSM(f32x16& p0, f32x16& p1, float& m_reg, float& mn, float& alpha) {
;   constexpr float C = SCALE * 1.4426950408889634f;
;   float pmax = p0[0];
; #pragma unroll
;   for (int r = 1; r < 16; ++r) pmax = fmaxf(pmax, p0[r]);
; #pragma unroll
;   for (int r = 0; r < 16; ++r) pmax = fmaxf(pmax, p1[r]);
;   { auto rr = __builtin_amdgcn_permlane32_swap(__float_as_uint(pmax), __float_as_uint(pmax), false, false);
;     pmax = fmaxf(__uint_as_float(rr[0]), __uint_as_float(rr[1])); }
;   if (__builtin_expect(__all(pmax - m_reg <= THR / SCALE), 1)) { mn = m_reg; alpha = 1.f; }
;   else { mn = fmaxf(m_reg, pmax); alpha = __builtin_amdgcn_exp2f((m_reg - mn) * C); m_reg = mn; }
; template <int MODE, int SDEPTH>
; __device__ __forceinline__ void attn_unit(const UnitP& u, char* lds) {
;     ...
;   f32x16 pA0, pA1, pB0, pB1; float mnA, mnB, alA, alB; bf16x8 pa0, pa1, pa2, pa3; const int NT = u.NT;
;   constexpr int SE = 0, SO = SDEPTH - 1;
;   SLOAD(SE, ROW0(0)); asm volatile("s_waitcnt vmcnt(0)" ::: "memory"); SWRITE(0, SE); __syncthreads();
;   qkt(pA0, pA1, K_lds, qr, r32, hi); mask_tile<MODE>(pA0, pA1, u, 0, wid, r32, hi, biasL); partialSM(pA0, pA1, m_reg, mnA, alA);
;   SLOAD(SO, ROW0(1)); if constexpr (SDEPTH == 2) { if (2 < NT) SLOAD(SE, ROW0(2)); }
;   SWAIT(); SWRITE(1, SO); __syncthreads();
;   for (int j = 1; j + 1 < NT; j += 2) {
;     SBAR(); qkt(pB0, pB1, (bf16_t*)((char*)K_lds + SHM_K), qr, r32, hi);
;     finishSM(pA0, pA1, alA, l_reg, pa0, pa1, pa2, pa3); SBAR();
;     SLOAD(SO, ROW0(j + SDEPTH)); SBAR();
;     pv_d0(o, vb0, pa0, pa1, pa2, pa3); mask_tile<MODE>(pB0, pB1, u, j, wid, r32, hi, biasL); partialSM(pB0, pB1, m_reg, mnB, alB);
	ds_write_b128 v197, v[150:153] offset:16384
	ds_write_b128 v197, v[154:157] offset:24576
	ds_write_b128 v185, v[158:161] offset:16384
	ds_write_b128 v185, v[162:165] offset:24576
	s_nop 1
	global_load_dwordx4 v[134:137], v184, s[16:17]
	global_load_dwordx4 v[138:141], v184, s[2:3]
	global_load_dwordx4 v[142:145], v184, s[14:15]
	global_load_dwordx4 v[146:149], v184, s[10:11]
	s_add_u32 s16, s16, 0x60000
	s_addc_u32 s17, s17, 0
	s_add_u32 s2, s2, 0x60000
	s_addc_u32 s3, s3, 0
	s_add_u32 s14, s14, 0x60000
	s_addc_u32 s15, s15, 0
	s_add_u32 s10, s10, 0x60000
	s_addc_u32 s11, s11, 0
	global_load_dwordx4 v[186:189], v184, s[16:17]
	global_load_dwordx4 v[220:223], v184, s[2:3]
	global_load_dwordx4 v[246:249], v184, s[14:15]
	global_load_dwordx4 v[200:203], v184, s[10:11]
	s_add_u32 s16, s16, 0x60000
	s_addc_u32 s17, s17, 0
	s_add_u32 s2, s2, 0x60000
	s_addc_u32 s3, s3, 0
	s_add_u32 s14, s14, 0x60000
	s_addc_u32 s15, s15, 0
	s_add_u32 s10, s10, 0x60000
	s_addc_u32 s11, s11, 0
	v_mov_b32_e32 v0, 0
	v_mov_b32_e32 v1, 0
	v_mov_b32_e32 v2, 0
	v_mov_b32_e32 v3, 0
	v_mov_b32_e32 v4, 0
	v_mov_b32_e32 v5, 0
	v_mov_b32_e32 v6, 0
	v_mov_b32_e32 v7, 0
	v_mov_b32_e32 v8, 0
	v_mov_b32_e32 v9, 0
	v_mov_b32_e32 v10, 0
	v_mov_b32_e32 v11, 0
	v_mov_b32_e32 v12, 0
	v_mov_b32_e32 v13, 0
	v_mov_b32_e32 v14, 0
	v_mov_b32_e32 v15, 0
	v_mov_b32_e32 v48, 0
	v_mov_b32_e32 v49, 0
	v_mov_b32_e32 v50, 0
	v_mov_b32_e32 v51, 0
	v_mov_b32_e32 v52, 0
	v_mov_b32_e32 v53, 0
	v_mov_b32_e32 v54, 0
	v_mov_b32_e32 v55, 0
	v_mov_b32_e32 v56, 0
	v_mov_b32_e32 v57, 0
	v_mov_b32_e32 v58, 0
	v_mov_b32_e32 v59, 0
	v_mov_b32_e32 v60, 0
	v_mov_b32_e32 v61, 0
	v_mov_b32_e32 v62, 0
	v_mov_b32_e32 v63, 0
	v_mov_b32_e32 v32, 0
	v_mov_b32_e32 v33, 0
	v_mov_b32_e32 v34, 0
	v_mov_b32_e32 v35, 0
	v_mov_b32_e32 v36, 0
	v_mov_b32_e32 v37, 0
	v_mov_b32_e32 v38, 0
	v_mov_b32_e32 v39, 0
	v_mov_b32_e32 v40, 0
	v_mov_b32_e32 v41, 0
	v_mov_b32_e32 v42, 0
	v_mov_b32_e32 v43, 0
	v_mov_b32_e32 v44, 0
	v_mov_b32_e32 v45, 0
	v_mov_b32_e32 v46, 0
	v_mov_b32_e32 v47, 0
	v_mov_b32_e32 v16, 0
	v_mov_b32_e32 v17, 0
	v_mov_b32_e32 v18, 0
	v_mov_b32_e32 v19, 0
	v_mov_b32_e32 v20, 0
	v_mov_b32_e32 v21, 0
	v_mov_b32_e32 v22, 0
	v_mov_b32_e32 v23, 0
	v_mov_b32_e32 v24, 0
	v_mov_b32_e32 v25, 0
	v_mov_b32_e32 v26, 0
	v_mov_b32_e32 v27, 0
	v_mov_b32_e32 v28, 0
	v_mov_b32_e32 v29, 0
	v_mov_b32_e32 v30, 0
	v_mov_b32_e32 v31, 0
	s_waitcnt lgkmcnt(0)
	s_barrier
	ds_read_b128 v[150:153], v204 offset:0
	ds_read_b128 v[154:157], v204 offset:8192
	ds_read_b128 v[158:161], v205 offset:0
	ds_read_b128 v[162:165], v205 offset:8192
	ds_read_b128 v[228:231], v206 offset:0
	ds_read_b128 v[232:235], v206 offset:8192
	ds_read_b128 v[236:239], v207 offset:0
	ds_read_b128 v[240:243], v207 offset:8192
	s_cmp_lt_u32 s36, 4
	s_cbranch_scc1 .Lda_lead
	s_barrier
.Lda_lead:
	s_setprio 3
	s_waitcnt vmcnt(4)
	ds_write_b128 v197, v[134:137] offset:32768
	ds_write_b128 v197, v[138:141] offset:40960
	ds_write_b128 v185, v[142:145] offset:32768
	ds_write_b128 v185, v[146:149] offset:40960
	s_waitcnt lgkmcnt(10)
	v_mfma_f32_32x32x16_bf16 v[80:95], v[150:153], v[130:133], 0
	v_mfma_f32_32x32x16_bf16 v[64:79], v[154:157], v[130:133], 0
	global_load_dwordx4 v[134:137], v184, s[16:17]
	global_load_dwordx4 v[138:141], v184, s[2:3]
	global_load_dwordx4 v[142:145], v184, s[14:15]
	global_load_dwordx4 v[146:149], v184, s[10:11]
	s_add_u32 s16, s16, 0x60000
	s_addc_u32 s17, s17, 0
	s_add_u32 s2, s2, 0x60000
	s_addc_u32 s3, s3, 0
	s_add_u32 s14, s14, 0x60000
	s_addc_u32 s15, s15, 0
	s_add_u32 s10, s10, 0x60000
	s_addc_u32 s11, s11, 0
	ds_read_b128 v[150:153], v208 offset:0
	ds_read_b128 v[154:157], v208 offset:8192
	s_waitcnt lgkmcnt(10)
	v_mfma_f32_32x32x16_bf16 v[80:95], v[158:161], v[126:129], v[80:95]
	v_mfma_f32_32x32x16_bf16 v[64:79], v[162:165], v[126:129], v[64:79]
	ds_read_b128 v[158:161], v209 offset:0
	ds_read_b128 v[162:165], v209 offset:8192
	s_waitcnt lgkmcnt(10)
	v_mfma_f32_32x32x16_bf16 v[80:95], v[228:231], v[122:125], v[80:95]
	v_mfma_f32_32x32x16_bf16 v[64:79], v[232:235], v[122:125], v[64:79]
	ds_read_b128 v[228:231], v210 offset:0
	ds_read_b128 v[232:235], v210 offset:8192
	s_waitcnt lgkmcnt(10)
	v_mfma_f32_32x32x16_bf16 v[80:95], v[236:239], v[118:121], v[80:95]
	v_mfma_f32_32x32x16_bf16 v[64:79], v[240:243], v[118:121], v[64:79]
	ds_read_b128 v[236:239], v211 offset:0
	ds_read_b128 v[240:243], v211 offset:8192
	s_waitcnt lgkmcnt(6)
	v_mfma_f32_32x32x16_bf16 v[80:95], v[150:153], v[114:117], v[80:95]
	v_mfma_f32_32x32x16_bf16 v[64:79], v[154:157], v[114:117], v[64:79]
	s_waitcnt lgkmcnt(4)
	v_mfma_f32_32x32x16_bf16 v[80:95], v[158:161], v[110:113], v[80:95]
	v_mfma_f32_32x32x16_bf16 v[64:79], v[162:165], v[110:113], v[64:79]
	s_waitcnt lgkmcnt(2)
	v_mfma_f32_32x32x16_bf16 v[80:95], v[228:231], v[106:109], v[80:95]
	v_mfma_f32_32x32x16_bf16 v[64:79], v[232:235], v[106:109], v[64:79]
	s_waitcnt lgkmcnt(0)
	v_mfma_f32_32x32x16_bf16 v[80:95], v[236:239], v[102:105], v[80:95]
	v_mfma_f32_32x32x16_bf16 v[64:79], v[240:243], v[102:105], v[64:79]
	s_nop 12
	v_max3_f32 v190, v80, v81, v82
	v_max3_f32 v191, v64, v65, v66
	v_max3_f32 v190, v190, v83, v84
	v_max3_f32 v191, v191, v67, v68
	v_max3_f32 v190, v190, v85, v86
	v_max3_f32 v191, v191, v69, v70
	v_max3_f32 v190, v190, v87, v88
	v_max3_f32 v191, v191, v71, v72
	v_max3_f32 v190, v190, v89, v90
	v_max3_f32 v191, v191, v73, v74
	v_max3_f32 v190, v190, v91, v92
	v_max3_f32 v191, v191, v75, v76
	v_max3_f32 v190, v190, v93, v94
	v_max3_f32 v191, v191, v77, v78
	v_max3_f32 v190, v190, v95, v79
	v_max_f32_e32 v190, v190, v191
	v_mov_b32_e32 v191, v190
	s_nop 1
	v_permlane32_swap_b32_e32 v190, v191
	s_nop 0
	v_max_f32_e32 v212, v190, v191
	v_sub_f32_e32 v190, v212, v174
	v_cmp_ge_f32_e32 vcc, s86, v190
	v_max_f32_e32 v191, v174, v212
	v_sub_f32_e32 v215, v174, v191
	v_mul_f32_e32 v215, s92, v215
	s_nop 1
	s_cmp_eq_u64 vcc, exec
	s_cselect_b64 s[42:43], -1, 0
	v_exp_f32_e32 v213, v215
	s_nop 0
	v_cndmask_b32_e64 v174, v191, v174, s[42:43]
	v_cndmask_b32_e64 v213, v213, 1.0, s[42:43]
	v_mul_f32_e32 v214, 0xbe0293ee, v174
	s_setprio 0
	s_branch .Lda_y0
; __device__ __forceinline__ void partialSM(f32x16& p0, f32x16& p1, float& m_reg, float& mn, float& alpha) {
; __device__ __forceinline__ void qkt(f32x16& p0, f32x16& p1, const bf16_t* Ks, const bf16x8* qr, int r32, int hi) {
;   p0 = f32x16{}; p1 = f32x16{};
; #pragma unroll
;   for (int d0 = 0; d0 < 8; ++d0) { int cb = (d0 * 16 + hi * 8) * 2;
;     bf16x8 b0 = *reinterpret_cast<const bf16x8*>((const char*)Ks + KSWZ(r32, cb));
;     bf16x8 b1 = *reinterpret_cast<const bf16x8*>((const char*)Ks + KSWZ(32 + r32, cb));
;     p0 = __builtin_amdgcn_mfma_f32_32x32x16_bf16(b0, qr[d0], p0, 0, 0, 0);
;     p1 = __builtin_amdgcn_mfma_f32_32x32x16_bf16(b1, qr[d0], p1, 0, 0, 0); }
; }
; __device__ __forceinline__ int v_st(int k, int c) { const int kk = (k & ~0xC) | ((k & 4) << 1) | ((k & 8) >> 1); return ((kk >> 3) * 4 + (c >> 5)) * 512 + ((kk & 7) * 32 + (c & 31)) * 2; }
; __device__ __forceinline__ int v_rd_base(int lane) { return ((lane & 3) << 3) | (((lane >> 2) & 3) << 6) | (((lane >> 4) & 1) << 5) | (((lane >> 5) & 1) << 8); }
; template <int OFF> __device__ __forceinline__ s16x4 tr_read(int vb) {
;   s16x4 r; asm volatile("ds_read_b64_tr_b16 %0, %1 offset:%2" : "=&v"(r) : "v"(vb), "i"(OFF) : "memory"); return r;
; }
; template <int D0> __device__ __forceinline__ void pv_one(f32x16& od, int vb, bf16x8 pa0, bf16x8 pa1, bf16x8 pa2, bf16x8 pa3) {
;   const s16x4 l0 = tr_read<v_rd_off(D0, 0, 0)>(vb), h0 = tr_read<v_rd_off(D0, 0, 1)>(vb), l1 = tr_read<v_rd_off(D0, 1, 0)>(vb), h1 = tr_read<v_rd_off(D0, 1, 1)>(vb);
;   const s16x4 l2 = tr_read<v_rd_off(D0, 2, 0)>(vb), h2 = tr_read<v_rd_off(D0, 2, 1)>(vb), l3 = tr_read<v_rd_off(D0, 3, 0)>(vb), h3 = tr_read<v_rd_off(D0, 3, 1)>(vb);
;   asm volatile("s_waitcnt lgkmcnt(0)" ::: "memory"); SBAR();
;     ...
;   od = __builtin_amdgcn_mfma_f32_32x32x16_bf16(pa0, PK(l0, h0), od, 0, 0, 0);
;   od = __builtin_amdgcn_mfma_f32_32x32x16_bf16(pa1, PK(l1, h1), od, 0, 0, 0);
;   od = __builtin_amdgcn_mfma_f32_32x32x16_bf16(pa2, PK(l2, h2), od, 0, 0, 0);
;   od = __builtin_amdgcn_mfma_f32_32x32x16_bf16(pa3, PK(l3, h3), od, 0, 0, 0);
;     ...
; }
; __device__ __forceinline__ void pv_d0(f32x16* o, int vb, bf16x8 pa0, bf16x8 pa1, bf16x8 pa2, bf16x8 pa3) {
;   pv_one<0>(o[0], vb, pa0, pa1, pa2, pa3); pv_one<1>(o[1], vb, pa0, pa1, pa2, pa3); pv_one<2>(o[2], vb, pa0, pa1, pa2, pa3); pv_one<3>(o[3], vb, pa0, pa1, pa2, pa3);
.Lda_loop:
	s_setprio 3
	s_waitcnt vmcnt(4)
	ds_write_b128 v197, v[134:137] offset:32768
	ds_write_b128 v197, v[138:141] offset:40960
	ds_write_b128 v185, v[142:145] offset:32768
	ds_write_b128 v185, v[146:149] offset:40960
	s_waitcnt lgkmcnt(10)
	v_mfma_f32_32x32x16_bf16 v[80:95], v[150:153], v[130:133], 0
	v_mfma_f32_32x32x16_bf16 v[64:79], v[154:157], v[130:133], 0
	global_load_dwordx4 v[134:137], v184, s[16:17]
	global_load_dwordx4 v[138:141], v184, s[2:3]
	global_load_dwordx4 v[142:145], v184, s[14:15]
	global_load_dwordx4 v[146:149], v184, s[10:11]
	s_add_u32 s16, s16, 0x60000
	s_addc_u32 s17, s17, 0
	s_add_u32 s2, s2, 0x60000
	s_addc_u32 s3, s3, 0
	s_add_u32 s14, s14, 0x60000
	s_addc_u32 s15, s15, 0
	s_add_u32 s10, s10, 0x60000
	s_addc_u32 s11, s11, 0
	ds_read_b128 v[150:153], v208 offset:0
	ds_read_b128 v[154:157], v208 offset:8192
	s_waitcnt lgkmcnt(10)
	v_mfma_f32_32x32x16_bf16 v[80:95], v[158:161], v[126:129], v[80:95]
	v_mfma_f32_32x32x16_bf16 v[64:79], v[162:165], v[126:129], v[64:79]
	ds_read_b128 v[158:161], v209 offset:0
	ds_read_b128 v[162:165], v209 offset:8192
	s_waitcnt lgkmcnt(10)
	v_mfma_f32_32x32x16_bf16 v[80:95], v[228:231], v[122:125], v[80:95]
	v_mfma_f32_32x32x16_bf16 v[64:79], v[232:235], v[122:125], v[64:79]
	ds_read_b128 v[228:231], v210 offset:0
	ds_read_b128 v[232:235], v210 offset:8192
	s_waitcnt lgkmcnt(10)
	v_mfma_f32_32x32x16_bf16 v[80:95], v[236:239], v[118:121], v[80:95]
	v_mfma_f32_32x32x16_bf16 v[64:79], v[240:243], v[118:121], v[64:79]
	ds_read_b128 v[236:239], v211 offset:0
	ds_read_b128 v[240:243], v211 offset:8192
	s_waitcnt lgkmcnt(6)
	v_mfma_f32_32x32x16_bf16 v[80:95], v[150:153], v[114:117], v[80:95]
	v_mfma_f32_32x32x16_bf16 v[64:79], v[154:157], v[114:117], v[64:79]
	ds_read_b64_tr_b16 v[150:151], v196 offset:49152
	ds_read_b64_tr_b16 v[152:153], v196 offset:51200
	ds_read_b64_tr_b16 v[154:155], v196 offset:53248
	ds_read_b64_tr_b16 v[156:157], v196 offset:55296
	s_waitcnt lgkmcnt(8)
	v_mfma_f32_32x32x16_bf16 v[80:95], v[158:161], v[110:113], v[80:95]
	v_mfma_f32_32x32x16_bf16 v[64:79], v[162:165], v[110:113], v[64:79]
	ds_read_b64_tr_b16 v[158:159], v196 offset:57344
	ds_read_b64_tr_b16 v[160:161], v196 offset:59392
	ds_read_b64_tr_b16 v[162:163], v196 offset:61440
	ds_read_b64_tr_b16 v[164:165], v196 offset:63488
	s_waitcnt lgkmcnt(10)
	v_mfma_f32_32x32x16_bf16 v[80:95], v[228:231], v[106:109], v[80:95]
	v_mfma_f32_32x32x16_bf16 v[64:79], v[232:235], v[106:109], v[64:79]
	ds_read_b64_tr_b16 v[228:229], v196 offset:49664
	ds_read_b64_tr_b16 v[230:231], v196 offset:51712
	ds_read_b64_tr_b16 v[232:233], v196 offset:53760
	ds_read_b64_tr_b16 v[234:235], v196 offset:55808
	s_waitcnt lgkmcnt(12)
	v_mfma_f32_32x32x16_bf16 v[80:95], v[236:239], v[102:105], v[80:95]
	v_mfma_f32_32x32x16_bf16 v[64:79], v[240:243], v[102:105], v[64:79]
	ds_read_b64_tr_b16 v[236:237], v196 offset:57856
	ds_read_b64_tr_b16 v[238:239], v196 offset:59904
	s_waitcnt lgkmcnt(12)
	v_mfma_f32_32x32x16_bf16 v[0:15], v[166:169], v[150:153], v[0:15]
	ds_read_b64_tr_b16 v[240:241], v196 offset:61952
	ds_read_b64_tr_b16 v[242:243], v196 offset:64000
	s_waitcnt lgkmcnt(12)
	v_mfma_f32_32x32x16_bf16 v[0:15], v[170:173], v[154:157], v[0:15]
	ds_read_b64_tr_b16 v[150:151], v196 offset:50176
	ds_read_b64_tr_b16 v[152:153], v196 offset:52224
	s_waitcnt lgkmcnt(12)
	v_mfma_f32_32x32x16_bf16 v[0:15], v[176:179], v[158:161], v[0:15]
	ds_read_b64_tr_b16 v[154:155], v196 offset:54272
	ds_read_b64_tr_b16 v[156:157], v196 offset:56320
	s_waitcnt lgkmcnt(12)
	v_mfma_f32_32x32x16_bf16 v[0:15], v[180:183], v[162:165], v[0:15]
	ds_read_b64_tr_b16 v[158:159], v196 offset:58368
	ds_read_b64_tr_b16 v[160:161], v196 offset:60416
	v_max3_f32 v190, v80, v81, v82
	v_max3_f32 v191, v64, v65, v66
	s_waitcnt lgkmcnt(12)
	v_mfma_f32_32x32x16_bf16 v[48:63], v[166:169], v[228:231], v[48:63]
	ds_read_b64_tr_b16 v[162:163], v196 offset:62464
	ds_read_b64_tr_b16 v[164:165], v196 offset:64512
	v_max3_f32 v190, v190, v83, v84
	v_max3_f32 v191, v191, v67, v68
	s_waitcnt lgkmcnt(12)
	v_mfma_f32_32x32x16_bf16 v[48:63], v[170:173], v[232:235], v[48:63]
	ds_read_b64_tr_b16 v[228:229], v196 offset:50688
	ds_read_b64_tr_b16 v[230:231], v196 offset:52736
	v_max3_f32 v190, v190, v85, v86
	v_max3_f32 v191, v191, v69, v70
	s_waitcnt lgkmcnt(12)
	v_mfma_f32_32x32x16_bf16 v[48:63], v[176:179], v[236:239], v[48:63]
	ds_read_b64_tr_b16 v[232:233], v196 offset:54784
	ds_read_b64_tr_b16 v[234:235], v196 offset:56832
	v_max3_f32 v190, v190, v87, v88
	v_max3_f32 v191, v191, v71, v72
	s_waitcnt lgkmcnt(12)
	v_mfma_f32_32x32x16_bf16 v[48:63], v[180:183], v[240:243], v[48:63]
	ds_read_b64_tr_b16 v[236:237], v196 offset:58880
	ds_read_b64_tr_b16 v[238:239], v196 offset:60928
	v_max3_f32 v190, v190, v89, v90
	v_max3_f32 v191, v191, v73, v74
	s_waitcnt lgkmcnt(12)
	v_mfma_f32_32x32x16_bf16 v[32:47], v[166:169], v[150:153], v[32:47]
	ds_read_b64_tr_b16 v[240:241], v196 offset:62976
	ds_read_b64_tr_b16 v[242:243], v196 offset:65024
	v_max3_f32 v190, v190, v91, v92
	v_max3_f32 v191, v191, v75, v76
	s_waitcnt lgkmcnt(12)
	v_mfma_f32_32x32x16_bf16 v[32:47], v[170:173], v[154:157], v[32:47]
	v_max3_f32 v190, v190, v93, v94
	v_max3_f32 v191, v191, v77, v78
	s_waitcnt lgkmcnt(10)
	v_mfma_f32_32x32x16_bf16 v[32:47], v[176:179], v[158:161], v[32:47]
	v_max3_f32 v190, v190, v95, v79
	v_max_f32_e32 v190, v190, v191
	s_waitcnt lgkmcnt(8)
	v_mfma_f32_32x32x16_bf16 v[32:47], v[180:183], v[162:165], v[32:47]
	v_mov_b32_e32 v191, v190
	s_nop 1
	v_permlane32_swap_b32_e32 v190, v191
	s_nop 0
	v_max_f32_e32 v212, v190, v191
	s_waitcnt lgkmcnt(6)
	v_mfma_f32_32x32x16_bf16 v[16:31], v[166:169], v[228:231], v[16:31]
	v_sub_f32_e32 v190, v212, v174
	v_cmp_ge_f32_e32 vcc, s86, v190
	v_max_f32_e32 v191, v174, v212
	v_sub_f32_e32 v215, v174, v191
	v_mul_f32_e32 v215, s92, v215
	s_waitcnt lgkmcnt(4)
	v_mfma_f32_32x32x16_bf16 v[16:31], v[170:173], v[232:235], v[16:31]
	s_nop 1
	s_cmp_eq_u64 vcc, exec
	s_cselect_b64 s[42:43], -1, 0
	s_waitcnt lgkmcnt(2)
	v_mfma_f32_32x32x16_bf16 v[16:31], v[176:179], v[236:239], v[16:31]
	v_exp_f32_e32 v213, v215
	s_nop 0
	v_cndmask_b32_e64 v174, v191, v174, s[42:43]
	s_waitcnt lgkmcnt(0)
	v_mfma_f32_32x32x16_bf16 v[16:31], v[180:183], v[240:243], v[16:31]
	v_cndmask_b32_e64 v213, v213, 1.0, s[42:43]
	v_mul_f32_e32 v214, 0xbe0293ee, v174
	s_setprio 0
; __device__ __forceinline__ void partialSM(f32x16& p0, f32x16& p1, float& m_reg, float& mn, float& alpha) {
;     ...
;   float mnC = -mn * C;
; #pragma unroll
;   for (int r = 0; r < 16; ++r) p0[r] = fmaf(p0[r], C, mnC);
; #pragma unroll
;   for (int r = 0; r < 16; ++r) p1[r] = fmaf(p1[r], C, mnC);
; #pragma unroll
;   for (int r = 0; r < 16; ++r) p0[r] = __builtin_amdgcn_exp2f(p0[r]);
; }
; __device__ __forceinline__ void finishSM(f32x16& p0, f32x16& p1, float alpha, float& l_reg, bf16x8& pa0, bf16x8& pa1, bf16x8& pa2, bf16x8& pa3) {
; #pragma unroll
;   for (int r = 0; r < 16; ++r) p1[r] = __builtin_amdgcn_exp2f(p1[r]);
;   float ps = 0;
; #pragma unroll
;   for (int r = 0; r < 16; ++r) ps += p0[r];
; #pragma unroll
;   for (int r = 0; r < 16; ++r) ps += p1[r];
;   { auto rr = __builtin_amdgcn_permlane32_swap(__float_as_uint(ps), __float_as_uint(ps), false, false);
;     ps = __uint_as_float(rr[0]) + __uint_as_float(rr[1]); }
;   l_reg = l_reg * alpha + ps;
;     ...
;   PK4(p0, 0, pa0); PK4(p0, 8, pa1); PK4(p1, 0, pa2); PK4(p1, 8, pa3);
;     ...
; }
.Lda_y0:
	s_barrier
	v_cmp_gt_f32_e32 vcc, 1.0, v213
	v_fma_f32 v80, v80, s92, v214
	v_fma_f32 v81, v81, s92, v214
	v_fma_f32 v82, v82, s92, v214
	v_fma_f32 v83, v83, s92, v214
	v_fma_f32 v84, v84, s92, v214
	v_fma_f32 v85, v85, s92, v214
	v_fma_f32 v86, v86, s92, v214
	v_fma_f32 v87, v87, s92, v214
	v_fma_f32 v88, v88, s92, v214
	v_fma_f32 v89, v89, s92, v214
	v_fma_f32 v90, v90, s92, v214
	v_fma_f32 v91, v91, s92, v214
	v_fma_f32 v92, v92, s92, v214
	v_fma_f32 v93, v93, s92, v214
	v_fma_f32 v94, v94, s92, v214
	v_fma_f32 v95, v95, s92, v214
	v_fma_f32 v64, v64, s92, v214
	v_fma_f32 v65, v65, s92, v214
	v_fma_f32 v66, v66, s92, v214
	v_fma_f32 v67, v67, s92, v214
	v_fma_f32 v68, v68, s92, v214
	v_fma_f32 v69, v69, s92, v214
	v_fma_f32 v70, v70, s92, v214
	v_fma_f32 v71, v71, s92, v214
	v_fma_f32 v72, v72, s92, v214
	v_fma_f32 v73, v73, s92, v214
	v_fma_f32 v74, v74, s92, v214
	v_fma_f32 v75, v75, s92, v214
	v_fma_f32 v76, v76, s92, v214
	v_fma_f32 v77, v77, s92, v214
	v_fma_f32 v78, v78, s92, v214
	v_fma_f32 v79, v79, s92, v214
	s_cbranch_vccz .Lda_noresc_0
	s_and_saveexec_b64 s[12:13], s[40:41]
	ds_write_b32 v199, v213 offset:128
	s_or_b64 exec, exec, s[12:13]
	s_waitcnt lgkmcnt(0)
	v_add_u32_e32 v215, v99, v96
	ds_read_b128 v[228:231], v215 offset:128
	ds_read_b128 v[232:235], v215 offset:160
	ds_read_b128 v[236:239], v215 offset:192
	ds_read_b128 v[240:243], v215 offset:224
	s_waitcnt lgkmcnt(0)
	v_pk_mul_f32 v[0:1], v[0:1], v[228:229]
	v_pk_mul_f32 v[2:3], v[2:3], v[230:231]
	v_pk_mul_f32 v[4:5], v[4:5], v[232:233]
	v_pk_mul_f32 v[6:7], v[6:7], v[234:235]
	v_pk_mul_f32 v[8:9], v[8:9], v[236:237]
	v_pk_mul_f32 v[10:11], v[10:11], v[238:239]
	v_pk_mul_f32 v[12:13], v[12:13], v[240:241]
	v_pk_mul_f32 v[14:15], v[14:15], v[242:243]
	v_pk_mul_f32 v[48:49], v[48:49], v[228:229]
	v_pk_mul_f32 v[50:51], v[50:51], v[230:231]
	v_pk_mul_f32 v[52:53], v[52:53], v[232:233]
	v_pk_mul_f32 v[54:55], v[54:55], v[234:235]
	v_pk_mul_f32 v[56:57], v[56:57], v[236:237]
	v_pk_mul_f32 v[58:59], v[58:59], v[238:239]
	v_pk_mul_f32 v[60:61], v[60:61], v[240:241]
	v_pk_mul_f32 v[62:63], v[62:63], v[242:243]
	v_pk_mul_f32 v[32:33], v[32:33], v[228:229]
	v_pk_mul_f32 v[34:35], v[34:35], v[230:231]
	v_pk_mul_f32 v[36:37], v[36:37], v[232:233]
	v_pk_mul_f32 v[38:39], v[38:39], v[234:235]
	v_pk_mul_f32 v[40:41], v[40:41], v[236:237]
	v_pk_mul_f32 v[42:43], v[42:43], v[238:239]
	v_pk_mul_f32 v[44:45], v[44:45], v[240:241]
	v_pk_mul_f32 v[46:47], v[46:47], v[242:243]
	v_pk_mul_f32 v[16:17], v[16:17], v[228:229]
	v_pk_mul_f32 v[18:19], v[18:19], v[230:231]
	v_pk_mul_f32 v[20:21], v[20:21], v[232:233]
	v_pk_mul_f32 v[22:23], v[22:23], v[234:235]
	v_pk_mul_f32 v[24:25], v[24:25], v[236:237]
	v_pk_mul_f32 v[26:27], v[26:27], v[238:239]
	v_pk_mul_f32 v[28:29], v[28:29], v[240:241]
	v_pk_mul_f32 v[30:31], v[30:31], v[242:243]
.Lda_noresc_0:
	v_exp_f32_e32 v80, v80
	v_exp_f32_e32 v81, v81
	v_exp_f32_e32 v82, v82
	v_exp_f32_e32 v83, v83
	v_exp_f32_e32 v84, v84
	v_exp_f32_e32 v85, v85
	v_exp_f32_e32 v86, v86
	v_exp_f32_e32 v87, v87
	v_exp_f32_e32 v88, v88
	v_exp_f32_e32 v89, v89
	v_exp_f32_e32 v90, v90
	v_exp_f32_e32 v91, v91
	v_exp_f32_e32 v92, v92
	v_exp_f32_e32 v93, v93
	v_exp_f32_e32 v94, v94
	v_exp_f32_e32 v95, v95
	v_exp_f32_e32 v64, v64
	v_exp_f32_e32 v65, v65
	v_exp_f32_e32 v66, v66
	v_exp_f32_e32 v67, v67
	v_exp_f32_e32 v68, v68
	v_exp_f32_e32 v69, v69
	v_exp_f32_e32 v70, v70
	v_exp_f32_e32 v71, v71
	v_exp_f32_e32 v72, v72
	v_exp_f32_e32 v73, v73
	v_exp_f32_e32 v74, v74
	v_exp_f32_e32 v75, v75
	v_exp_f32_e32 v76, v76
	v_exp_f32_e32 v77, v77
	v_exp_f32_e32 v78, v78
	v_exp_f32_e32 v79, v79
	v_add_f32_e32 v190, v80, v81
	v_add_f32_e32 v191, v82, v83
	v_add_f32_e32 v190, v190, v84
	v_add_f32_e32 v191, v191, v85
	v_add_f32_e32 v190, v190, v86
	v_add_f32_e32 v191, v191, v87
	v_add_f32_e32 v190, v190, v88
	v_add_f32_e32 v191, v191, v89
	v_add_f32_e32 v190, v190, v90
	v_add_f32_e32 v191, v191, v91
	v_add_f32_e32 v190, v190, v92
	v_add_f32_e32 v191, v191, v93
	v_add_f32_e32 v190, v190, v94
	v_add_f32_e32 v191, v191, v95
	v_add_f32_e32 v190, v190, v64
	v_add_f32_e32 v191, v191, v65
	v_add_f32_e32 v190, v190, v66
	v_add_f32_e32 v191, v191, v67
	v_add_f32_e32 v190, v190, v68
	v_add_f32_e32 v191, v191, v69
	v_add_f32_e32 v190, v190, v70
	v_add_f32_e32 v191, v191, v71
	v_add_f32_e32 v190, v190, v72
	v_add_f32_e32 v191, v191, v73
	v_add_f32_e32 v190, v190, v74
	v_add_f32_e32 v191, v191, v75
	v_add_f32_e32 v190, v190, v76
	v_add_f32_e32 v191, v191, v77
	v_add_f32_e32 v190, v190, v78
	v_add_f32_e32 v191, v191, v79
	v_add_f32_e32 v190, v190, v191
	v_mov_b32_e32 v191, v190
	v_cvt_pk_bf16_f32 v166, v80, v81
	v_cvt_pk_bf16_f32 v167, v82, v83
	v_cvt_pk_bf16_f32 v168, v84, v85
	v_cvt_pk_bf16_f32 v169, v86, v87
	v_cvt_pk_bf16_f32 v170, v88, v89
	v_cvt_pk_bf16_f32 v171, v90, v91
	v_cvt_pk_bf16_f32 v172, v92, v93
	v_cvt_pk_bf16_f32 v173, v94, v95
	v_cvt_pk_bf16_f32 v176, v64, v65
	v_cvt_pk_bf16_f32 v177, v66, v67
	v_cvt_pk_bf16_f32 v178, v68, v69
	v_cvt_pk_bf16_f32 v179, v70, v71
	v_cvt_pk_bf16_f32 v180, v72, v73
	v_cvt_pk_bf16_f32 v181, v74, v75
	v_cvt_pk_bf16_f32 v182, v76, v77
	v_cvt_pk_bf16_f32 v183, v78, v79
	s_nop 1
	v_permlane32_swap_b32_e32 v190, v191
	v_permlane32_swap_b32_e32 v166, v168
	v_permlane32_swap_b32_e32 v167, v169
	v_permlane32_swap_b32_e32 v170, v172
	v_permlane32_swap_b32_e32 v171, v173
	v_permlane32_swap_b32_e32 v176, v178
	v_permlane32_swap_b32_e32 v177, v179
	v_permlane32_swap_b32_e32 v180, v182
	v_permlane32_swap_b32_e32 v181, v183
	v_add_f32_e32 v190, v190, v191
	v_fma_f32 v175, v175, v213, v190
	s_add_u32 s31, s31, 1
	s_cmp_lt_u32 s31, 132
	s_cbranch_scc0 .Lda_skipk_0
	ds_read_b128 v[150:153], v204 offset:16384
	ds_read_b128 v[154:157], v204 offset:24576
	ds_read_b128 v[158:161], v205 offset:16384
	ds_read_b128 v[162:165], v205 offset:24576
	ds_read_b128 v[228:231], v206 offset:16384
	ds_read_b128 v[232:235], v206 offset:24576
	ds_read_b128 v[236:239], v207 offset:16384
	ds_read_b128 v[240:243], v207 offset:24576
; __device__ __forceinline__ void partialSM(f32x16& p0, f32x16& p1, float& m_reg, float& mn, float& alpha) {
; __device__ __forceinline__ void qkt(f32x16& p0, f32x16& p1, const bf16_t* Ks, const bf16x8* qr, int r32, int hi) {
;   p0 = f32x16{}; p1 = f32x16{};
; #pragma unroll
;   for (int d0 = 0; d0 < 8; ++d0) { int cb = (d0 * 16 + hi * 8) * 2;
;     bf16x8 b0 = *reinterpret_cast<const bf16x8*>((const char*)Ks + KSWZ(r32, cb));
;     bf16x8 b1 = *reinterpret_cast<const bf16x8*>((const char*)Ks + KSWZ(32 + r32, cb));
;     p0 = __builtin_amdgcn_mfma_f32_32x32x16_bf16(b0, qr[d0], p0, 0, 0, 0);
;     p1 = __builtin_amdgcn_mfma_f32_32x32x16_bf16(b1, qr[d0], p1, 0, 0, 0); }
; }
; __device__ __forceinline__ int v_st(int k, int c) { const int kk = (k & ~0xC) | ((k & 4) << 1) | ((k & 8) >> 1); return ((kk >> 3) * 4 + (c >> 5)) * 512 + ((kk & 7) * 32 + (c & 31)) * 2; }
; __device__ __forceinline__ int v_rd_base(int lane) { return ((lane & 3) << 3) | (((lane >> 2) & 3) << 6) | (((lane >> 4) & 1) << 5) | (((lane >> 5) & 1) << 8); }
; template <int OFF> __device__ __forceinline__ s16x4 tr_read(int vb) {
;   s16x4 r; asm volatile("ds_read_b64_tr_b16 %0, %1 offset:%2" : "=&v"(r) : "v"(vb), "i"(OFF) : "memory"); return r;
; }
; template <int D0> __device__ __forceinline__ void pv_one(f32x16& od, int vb, bf16x8 pa0, bf16x8 pa1, bf16x8 pa2, bf16x8 pa3) {
;   const s16x4 l0 = tr_read<v_rd_off(D0, 0, 0)>(vb), h0 = tr_read<v_rd_off(D0, 0, 1)>(vb), l1 = tr_read<v_rd_off(D0, 1, 0)>(vb), h1 = tr_read<v_rd_off(D0, 1, 1)>(vb);
;   const s16x4 l2 = tr_read<v_rd_off(D0, 2, 0)>(vb), h2 = tr_read<v_rd_off(D0, 2, 1)>(vb), l3 = tr_read<v_rd_off(D0, 3, 0)>(vb), h3 = tr_read<v_rd_off(D0, 3, 1)>(vb);
;   asm volatile("s_waitcnt lgkmcnt(0)" ::: "memory"); SBAR();
;     ...
;   od = __builtin_amdgcn_mfma_f32_32x32x16_bf16(pa0, PK(l0, h0), od, 0, 0, 0);
;   od = __builtin_amdgcn_mfma_f32_32x32x16_bf16(pa1, PK(l1, h1), od, 0, 0, 0);
;   od = __builtin_amdgcn_mfma_f32_32x32x16_bf16(pa2, PK(l2, h2), od, 0, 0, 0);
;   od = __builtin_amdgcn_mfma_f32_32x32x16_bf16(pa3, PK(l3, h3), od, 0, 0, 0);
;     ...
; }
; __device__ __forceinline__ void pv_d0(f32x16* o, int vb, bf16x8 pa0, bf16x8 pa1, bf16x8 pa2, bf16x8 pa3) {
;   pv_one<0>(o[0], vb, pa0, pa1, pa2, pa3); pv_one<1>(o[1], vb, pa0, pa1, pa2, pa3); pv_one<2>(o[2], vb, pa0, pa1, pa2, pa3); pv_one<3>(o[3], vb, pa0, pa1, pa2, pa3);
.Lda_skipk_0:
	s_barrier
	s_setprio 3
	s_waitcnt vmcnt(4)
	ds_write_b128 v197, v[186:189] offset:49152
	ds_write_b128 v197, v[220:223] offset:57344
	ds_write_b128 v185, v[246:249] offset:49152
	ds_write_b128 v185, v[200:203] offset:57344
	s_waitcnt lgkmcnt(10)
	v_mfma_f32_32x32x16_bf16 v[80:95], v[150:153], v[130:133], 0
	v_mfma_f32_32x32x16_bf16 v[64:79], v[154:157], v[130:133], 0
	global_load_dwordx4 v[186:189], v184, s[16:17]
	global_load_dwordx4 v[220:223], v184, s[2:3]
	global_load_dwordx4 v[246:249], v184, s[14:15]
	global_load_dwordx4 v[200:203], v184, s[10:11]
	s_add_u32 s16, s16, 0x60000
	s_addc_u32 s17, s17, 0
	s_add_u32 s2, s2, 0x60000
	s_addc_u32 s3, s3, 0
	s_add_u32 s14, s14, 0x60000
	s_addc_u32 s15, s15, 0
	s_add_u32 s10, s10, 0x60000
	s_addc_u32 s11, s11, 0
	ds_read_b128 v[150:153], v208 offset:16384
	ds_read_b128 v[154:157], v208 offset:24576
	s_waitcnt lgkmcnt(10)
	v_mfma_f32_32x32x16_bf16 v[80:95], v[158:161], v[126:129], v[80:95]
	v_mfma_f32_32x32x16_bf16 v[64:79], v[162:165], v[126:129], v[64:79]
	ds_read_b128 v[158:161], v209 offset:16384
	ds_read_b128 v[162:165], v209 offset:24576
	s_waitcnt lgkmcnt(10)
	v_mfma_f32_32x32x16_bf16 v[80:95], v[228:231], v[122:125], v[80:95]
	v_mfma_f32_32x32x16_bf16 v[64:79], v[232:235], v[122:125], v[64:79]
	ds_read_b128 v[228:231], v210 offset:16384
	ds_read_b128 v[232:235], v210 offset:24576
	s_waitcnt lgkmcnt(10)
	v_mfma_f32_32x32x16_bf16 v[80:95], v[236:239], v[118:121], v[80:95]
	v_mfma_f32_32x32x16_bf16 v[64:79], v[240:243], v[118:121], v[64:79]
	ds_read_b128 v[236:239], v211 offset:16384
	ds_read_b128 v[240:243], v211 offset:24576
	s_waitcnt lgkmcnt(6)
	v_mfma_f32_32x32x16_bf16 v[80:95], v[150:153], v[114:117], v[80:95]
	v_mfma_f32_32x32x16_bf16 v[64:79], v[154:157], v[114:117], v[64:79]
	ds_read_b64_tr_b16 v[150:151], v196 offset:0
	ds_read_b64_tr_b16 v[152:153], v196 offset:2048
	ds_read_b64_tr_b16 v[154:155], v196 offset:4096
	ds_read_b64_tr_b16 v[156:157], v196 offset:6144
	s_waitcnt lgkmcnt(8)
	v_mfma_f32_32x32x16_bf16 v[80:95], v[158:161], v[110:113], v[80:95]
	v_mfma_f32_32x32x16_bf16 v[64:79], v[162:165], v[110:113], v[64:79]
	ds_read_b64_tr_b16 v[158:159], v196 offset:8192
	ds_read_b64_tr_b16 v[160:161], v196 offset:10240
	ds_read_b64_tr_b16 v[162:163], v196 offset:12288
	ds_read_b64_tr_b16 v[164:165], v196 offset:14336
	s_waitcnt lgkmcnt(10)
	v_mfma_f32_32x32x16_bf16 v[80:95], v[228:231], v[106:109], v[80:95]
	v_mfma_f32_32x32x16_bf16 v[64:79], v[232:235], v[106:109], v[64:79]
	ds_read_b64_tr_b16 v[228:229], v196 offset:512
	ds_read_b64_tr_b16 v[230:231], v196 offset:2560
	ds_read_b64_tr_b16 v[232:233], v196 offset:4608
	ds_read_b64_tr_b16 v[234:235], v196 offset:6656
	s_waitcnt lgkmcnt(12)
	v_mfma_f32_32x32x16_bf16 v[80:95], v[236:239], v[102:105], v[80:95]
	v_mfma_f32_32x32x16_bf16 v[64:79], v[240:243], v[102:105], v[64:79]
	ds_read_b64_tr_b16 v[236:237], v196 offset:8704
	ds_read_b64_tr_b16 v[238:239], v196 offset:10752
	s_waitcnt lgkmcnt(12)
	v_mfma_f32_32x32x16_bf16 v[0:15], v[166:169], v[150:153], v[0:15]
	ds_read_b64_tr_b16 v[240:241], v196 offset:12800
	ds_read_b64_tr_b16 v[242:243], v196 offset:14848
	s_waitcnt lgkmcnt(12)
	v_mfma_f32_32x32x16_bf16 v[0:15], v[170:173], v[154:157], v[0:15]
	ds_read_b64_tr_b16 v[150:151], v196 offset:1024
	ds_read_b64_tr_b16 v[152:153], v196 offset:3072
	s_waitcnt lgkmcnt(12)
	v_mfma_f32_32x32x16_bf16 v[0:15], v[176:179], v[158:161], v[0:15]
	ds_read_b64_tr_b16 v[154:155], v196 offset:5120
	ds_read_b64_tr_b16 v[156:157], v196 offset:7168
	s_waitcnt lgkmcnt(12)
	v_mfma_f32_32x32x16_bf16 v[0:15], v[180:183], v[162:165], v[0:15]
	ds_read_b64_tr_b16 v[158:159], v196 offset:9216
	ds_read_b64_tr_b16 v[160:161], v196 offset:11264
	v_max3_f32 v190, v80, v81, v82
	v_max3_f32 v191, v64, v65, v66
	s_waitcnt lgkmcnt(12)
	v_mfma_f32_32x32x16_bf16 v[48:63], v[166:169], v[228:231], v[48:63]
	ds_read_b64_tr_b16 v[162:163], v196 offset:13312
	ds_read_b64_tr_b16 v[164:165], v196 offset:15360
	v_max3_f32 v190, v190, v83, v84
	v_max3_f32 v191, v191, v67, v68
	s_waitcnt lgkmcnt(12)
	v_mfma_f32_32x32x16_bf16 v[48:63], v[170:173], v[232:235], v[48:63]
	ds_read_b64_tr_b16 v[228:229], v196 offset:1536
	ds_read_b64_tr_b16 v[230:231], v196 offset:3584
	v_max3_f32 v190, v190, v85, v86
	v_max3_f32 v191, v191, v69, v70
	s_waitcnt lgkmcnt(12)
	v_mfma_f32_32x32x16_bf16 v[48:63], v[176:179], v[236:239], v[48:63]
	ds_read_b64_tr_b16 v[232:233], v196 offset:5632
	ds_read_b64_tr_b16 v[234:235], v196 offset:7680
	v_max3_f32 v190, v190, v87, v88
	v_max3_f32 v191, v191, v71, v72
	s_waitcnt lgkmcnt(12)
	v_mfma_f32_32x32x16_bf16 v[48:63], v[180:183], v[240:243], v[48:63]
	ds_read_b64_tr_b16 v[236:237], v196 offset:9728
	ds_read_b64_tr_b16 v[238:239], v196 offset:11776
	v_max3_f32 v190, v190, v89, v90
	v_max3_f32 v191, v191, v73, v74
	s_waitcnt lgkmcnt(12)
	v_mfma_f32_32x32x16_bf16 v[32:47], v[166:169], v[150:153], v[32:47]
	ds_read_b64_tr_b16 v[240:241], v196 offset:13824
	ds_read_b64_tr_b16 v[242:243], v196 offset:15872
	v_max3_f32 v190, v190, v91, v92
	v_max3_f32 v191, v191, v75, v76
	s_waitcnt lgkmcnt(12)
	v_mfma_f32_32x32x16_bf16 v[32:47], v[170:173], v[154:157], v[32:47]
	v_max3_f32 v190, v190, v93, v94
	v_max3_f32 v191, v191, v77, v78
	s_waitcnt lgkmcnt(10)
	v_mfma_f32_32x32x16_bf16 v[32:47], v[176:179], v[158:161], v[32:47]
	v_max3_f32 v190, v190, v95, v79
	v_max_f32_e32 v190, v190, v191
	s_waitcnt lgkmcnt(8)
	v_mfma_f32_32x32x16_bf16 v[32:47], v[180:183], v[162:165], v[32:47]
	v_mov_b32_e32 v191, v190
	s_nop 1
	v_permlane32_swap_b32_e32 v190, v191
	s_nop 0
	v_max_f32_e32 v212, v190, v191
	s_waitcnt lgkmcnt(6)
	v_mfma_f32_32x32x16_bf16 v[16:31], v[166:169], v[228:231], v[16:31]
	v_sub_f32_e32 v190, v212, v174
	v_cmp_ge_f32_e32 vcc, s86, v190
	v_max_f32_e32 v191, v174, v212
	v_sub_f32_e32 v215, v174, v191
	v_mul_f32_e32 v215, s92, v215
	s_waitcnt lgkmcnt(4)
	v_mfma_f32_32x32x16_bf16 v[16:31], v[170:173], v[232:235], v[16:31]
	s_nop 1
	s_cmp_eq_u64 vcc, exec
	s_cselect_b64 s[42:43], -1, 0
	s_waitcnt lgkmcnt(2)
	v_mfma_f32_32x32x16_bf16 v[16:31], v[176:179], v[236:239], v[16:31]
	v_exp_f32_e32 v213, v215
	s_nop 0
	v_cndmask_b32_e64 v174, v191, v174, s[42:43]
	s_waitcnt lgkmcnt(0)
	v_mfma_f32_32x32x16_bf16 v[16:31], v[180:183], v[240:243], v[16:31]
	v_cndmask_b32_e64 v213, v213, 1.0, s[42:43]
	v_mul_f32_e32 v214, 0xbe0293ee, v174
	s_setprio 0
	s_barrier
; __device__ __forceinline__ void partialSM(f32x16& p0, f32x16& p1, float& m_reg, float& mn, float& alpha) {
;     ...
;   float mnC = -mn * C;
; #pragma unroll
;   for (int r = 0; r < 16; ++r) p0[r] = fmaf(p0[r], C, mnC);
; #pragma unroll
;   for (int r = 0; r < 16; ++r) p1[r] = fmaf(p1[r], C, mnC);
; #pragma unroll
;   for (int r = 0; r < 16; ++r) p0[r] = __builtin_amdgcn_exp2f(p0[r]);
; }
; __device__ __forceinline__ void finishSM(f32x16& p0, f32x16& p1, float alpha, float& l_reg, bf16x8& pa0, bf16x8& pa1, bf16x8& pa2, bf16x8& pa3) {
; #pragma unroll
;   for (int r = 0; r < 16; ++r) p1[r] = __builtin_amdgcn_exp2f(p1[r]);
;   float ps = 0;
; #pragma unroll
;   for (int r = 0; r < 16; ++r) ps += p0[r];
; #pragma unroll
;   for (int r = 0; r < 16; ++r) ps += p1[r];
;   { auto rr = __builtin_amdgcn_permlane32_swap(__float_as_uint(ps), __float_as_uint(ps), false, false);
;     ps = __uint_as_float(rr[0]) + __uint_as_float(rr[1]); }
;   l_reg = l_reg * alpha + ps;
;     ...
;   PK4(p0, 0, pa0); PK4(p0, 8, pa1); PK4(p1, 0, pa2); PK4(p1, 8, pa3);
;     ...
; }
	v_cmp_gt_f32_e32 vcc, 1.0, v213
	v_fma_f32 v80, v80, s92, v214
	v_fma_f32 v81, v81, s92, v214
	v_fma_f32 v82, v82, s92, v214
	v_fma_f32 v83, v83, s92, v214
	v_fma_f32 v84, v84, s92, v214
	v_fma_f32 v85, v85, s92, v214
	v_fma_f32 v86, v86, s92, v214
	v_fma_f32 v87, v87, s92, v214
	v_fma_f32 v88, v88, s92, v214
	v_fma_f32 v89, v89, s92, v214
	v_fma_f32 v90, v90, s92, v214
	v_fma_f32 v91, v91, s92, v214
	v_fma_f32 v92, v92, s92, v214
	v_fma_f32 v93, v93, s92, v214
	v_fma_f32 v94, v94, s92, v214
	v_fma_f32 v95, v95, s92, v214
	v_fma_f32 v64, v64, s92, v214
	v_fma_f32 v65, v65, s92, v214
	v_fma_f32 v66, v66, s92, v214
	v_fma_f32 v67, v67, s92, v214
	v_fma_f32 v68, v68, s92, v214
	v_fma_f32 v69, v69, s92, v214
	v_fma_f32 v70, v70, s92, v214
	v_fma_f32 v71, v71, s92, v214
	v_fma_f32 v72, v72, s92, v214
	v_fma_f32 v73, v73, s92, v214
	v_fma_f32 v74, v74, s92, v214
	v_fma_f32 v75, v75, s92, v214
	v_fma_f32 v76, v76, s92, v214
	v_fma_f32 v77, v77, s92, v214
	v_fma_f32 v78, v78, s92, v214
	v_fma_f32 v79, v79, s92, v214
	s_cbranch_vccz .Lda_noresc_1
	s_and_saveexec_b64 s[12:13], s[40:41]
	ds_write_b32 v199, v213 offset:128
	s_or_b64 exec, exec, s[12:13]
	s_waitcnt lgkmcnt(0)
	v_add_u32_e32 v215, v99, v96
	ds_read_b128 v[228:231], v215 offset:128
	ds_read_b128 v[232:235], v215 offset:160
	ds_read_b128 v[236:239], v215 offset:192
	ds_read_b128 v[240:243], v215 offset:224
	s_waitcnt lgkmcnt(0)
	v_pk_mul_f32 v[0:1], v[0:1], v[228:229]
	v_pk_mul_f32 v[2:3], v[2:3], v[230:231]
	v_pk_mul_f32 v[4:5], v[4:5], v[232:233]
	v_pk_mul_f32 v[6:7], v[6:7], v[234:235]
	v_pk_mul_f32 v[8:9], v[8:9], v[236:237]
	v_pk_mul_f32 v[10:11], v[10:11], v[238:239]
	v_pk_mul_f32 v[12:13], v[12:13], v[240:241]
	v_pk_mul_f32 v[14:15], v[14:15], v[242:243]
	v_pk_mul_f32 v[48:49], v[48:49], v[228:229]
	v_pk_mul_f32 v[50:51], v[50:51], v[230:231]
	v_pk_mul_f32 v[52:53], v[52:53], v[232:233]
	v_pk_mul_f32 v[54:55], v[54:55], v[234:235]
	v_pk_mul_f32 v[56:57], v[56:57], v[236:237]
	v_pk_mul_f32 v[58:59], v[58:59], v[238:239]
	v_pk_mul_f32 v[60:61], v[60:61], v[240:241]
	v_pk_mul_f32 v[62:63], v[62:63], v[242:243]
	v_pk_mul_f32 v[32:33], v[32:33], v[228:229]
	v_pk_mul_f32 v[34:35], v[34:35], v[230:231]
	v_pk_mul_f32 v[36:37], v[36:37], v[232:233]
	v_pk_mul_f32 v[38:39], v[38:39], v[234:235]
	v_pk_mul_f32 v[40:41], v[40:41], v[236:237]
	v_pk_mul_f32 v[42:43], v[42:43], v[238:239]
	v_pk_mul_f32 v[44:45], v[44:45], v[240:241]
	v_pk_mul_f32 v[46:47], v[46:47], v[242:243]
	v_pk_mul_f32 v[16:17], v[16:17], v[228:229]
	v_pk_mul_f32 v[18:19], v[18:19], v[230:231]
	v_pk_mul_f32 v[20:21], v[20:21], v[232:233]
	v_pk_mul_f32 v[22:23], v[22:23], v[234:235]
	v_pk_mul_f32 v[24:25], v[24:25], v[236:237]
	v_pk_mul_f32 v[26:27], v[26:27], v[238:239]
	v_pk_mul_f32 v[28:29], v[28:29], v[240:241]
	v_pk_mul_f32 v[30:31], v[30:31], v[242:243]
.Lda_noresc_1:
	v_exp_f32_e32 v80, v80
	v_exp_f32_e32 v81, v81
	v_exp_f32_e32 v82, v82
	v_exp_f32_e32 v83, v83
	v_exp_f32_e32 v84, v84
	v_exp_f32_e32 v85, v85
	v_exp_f32_e32 v86, v86
	v_exp_f32_e32 v87, v87
	v_exp_f32_e32 v88, v88
	v_exp_f32_e32 v89, v89
	v_exp_f32_e32 v90, v90
	v_exp_f32_e32 v91, v91
	v_exp_f32_e32 v92, v92
	v_exp_f32_e32 v93, v93
	v_exp_f32_e32 v94, v94
	v_exp_f32_e32 v95, v95
	v_exp_f32_e32 v64, v64
	v_exp_f32_e32 v65, v65
	v_exp_f32_e32 v66, v66
	v_exp_f32_e32 v67, v67
	v_exp_f32_e32 v68, v68
	v_exp_f32_e32 v69, v69
	v_exp_f32_e32 v70, v70
	v_exp_f32_e32 v71, v71
	v_exp_f32_e32 v72, v72
	v_exp_f32_e32 v73, v73
	v_exp_f32_e32 v74, v74
	v_exp_f32_e32 v75, v75
	v_exp_f32_e32 v76, v76
	v_exp_f32_e32 v77, v77
	v_exp_f32_e32 v78, v78
	v_exp_f32_e32 v79, v79
	v_add_f32_e32 v190, v80, v81
	v_add_f32_e32 v191, v82, v83
	v_add_f32_e32 v190, v190, v84
	v_add_f32_e32 v191, v191, v85
	v_add_f32_e32 v190, v190, v86
	v_add_f32_e32 v191, v191, v87
	v_add_f32_e32 v190, v190, v88
	v_add_f32_e32 v191, v191, v89
	v_add_f32_e32 v190, v190, v90
	v_add_f32_e32 v191, v191, v91
	v_add_f32_e32 v190, v190, v92
	v_add_f32_e32 v191, v191, v93
	v_add_f32_e32 v190, v190, v94
	v_add_f32_e32 v191, v191, v95
	v_add_f32_e32 v190, v190, v64
	v_add_f32_e32 v191, v191, v65
	v_add_f32_e32 v190, v190, v66
	v_add_f32_e32 v191, v191, v67
	v_add_f32_e32 v190, v190, v68
	v_add_f32_e32 v191, v191, v69
	v_add_f32_e32 v190, v190, v70
	v_add_f32_e32 v191, v191, v71
	v_add_f32_e32 v190, v190, v72
	v_add_f32_e32 v191, v191, v73
	v_add_f32_e32 v190, v190, v74
	v_add_f32_e32 v191, v191, v75
	v_add_f32_e32 v190, v190, v76
	v_add_f32_e32 v191, v191, v77
	v_add_f32_e32 v190, v190, v78
	v_add_f32_e32 v191, v191, v79
	v_add_f32_e32 v190, v190, v191
	v_mov_b32_e32 v191, v190
	v_cvt_pk_bf16_f32 v166, v80, v81
	v_cvt_pk_bf16_f32 v167, v82, v83
	v_cvt_pk_bf16_f32 v168, v84, v85
	v_cvt_pk_bf16_f32 v169, v86, v87
	v_cvt_pk_bf16_f32 v170, v88, v89
	v_cvt_pk_bf16_f32 v171, v90, v91
	v_cvt_pk_bf16_f32 v172, v92, v93
	v_cvt_pk_bf16_f32 v173, v94, v95
	v_cvt_pk_bf16_f32 v176, v64, v65
	v_cvt_pk_bf16_f32 v177, v66, v67
	v_cvt_pk_bf16_f32 v178, v68, v69
	v_cvt_pk_bf16_f32 v179, v70, v71
	v_cvt_pk_bf16_f32 v180, v72, v73
	v_cvt_pk_bf16_f32 v181, v74, v75
	v_cvt_pk_bf16_f32 v182, v76, v77
	v_cvt_pk_bf16_f32 v183, v78, v79
	s_nop 1
	v_permlane32_swap_b32_e32 v190, v191
	v_permlane32_swap_b32_e32 v166, v168
	v_permlane32_swap_b32_e32 v167, v169
	v_permlane32_swap_b32_e32 v170, v172
	v_permlane32_swap_b32_e32 v171, v173
	v_permlane32_swap_b32_e32 v176, v178
	v_permlane32_swap_b32_e32 v177, v179
	v_permlane32_swap_b32_e32 v180, v182
	v_permlane32_swap_b32_e32 v181, v183
	v_add_f32_e32 v190, v190, v191
	v_fma_f32 v175, v175, v213, v190
	s_add_u32 s31, s31, 1
	s_cmp_lt_u32 s31, 132
	s_cbranch_scc0 .Lda_skipk_1
	ds_read_b128 v[150:153], v204 offset:32768
	ds_read_b128 v[154:157], v204 offset:40960
	ds_read_b128 v[158:161], v205 offset:32768
	ds_read_b128 v[162:165], v205 offset:40960
	ds_read_b128 v[228:231], v206 offset:32768
	ds_read_b128 v[232:235], v206 offset:40960
	ds_read_b128 v[236:239], v207 offset:32768
	ds_read_b128 v[240:243], v207 offset:40960
; __device__ __forceinline__ void partialSM(f32x16& p0, f32x16& p1, float& m_reg, float& mn, float& alpha) {
; __device__ __forceinline__ void qkt(f32x16& p0, f32x16& p1, const bf16_t* Ks, const bf16x8* qr, int r32, int hi) {
;   p0 = f32x16{}; p1 = f32x16{};
; #pragma unroll
;   for (int d0 = 0; d0 < 8; ++d0) { int cb = (d0 * 16 + hi * 8) * 2;
;     bf16x8 b0 = *reinterpret_cast<const bf16x8*>((const char*)Ks + KSWZ(r32, cb));
;     bf16x8 b1 = *reinterpret_cast<const bf16x8*>((const char*)Ks + KSWZ(32 + r32, cb));
;     p0 = __builtin_amdgcn_mfma_f32_32x32x16_bf16(b0, qr[d0], p0, 0, 0, 0);
;     p1 = __builtin_amdgcn_mfma_f32_32x32x16_bf16(b1, qr[d0], p1, 0, 0, 0); }
; }
; __device__ __forceinline__ int v_st(int k, int c) { const int kk = (k & ~0xC) | ((k & 4) << 1) | ((k & 8) >> 1); return ((kk >> 3) * 4 + (c >> 5)) * 512 + ((kk & 7) * 32 + (c & 31)) * 2; }
; __device__ __forceinline__ int v_rd_base(int lane) { return ((lane & 3) << 3) | (((lane >> 2) & 3) << 6) | (((lane >> 4) & 1) << 5) | (((lane >> 5) & 1) << 8); }
; template <int OFF> __device__ __forceinline__ s16x4 tr_read(int vb) {
;   s16x4 r; asm volatile("ds_read_b64_tr_b16 %0, %1 offset:%2" : "=&v"(r) : "v"(vb), "i"(OFF) : "memory"); return r;
; }
; template <int D0> __device__ __forceinline__ void pv_one(f32x16& od, int vb, bf16x8 pa0, bf16x8 pa1, bf16x8 pa2, bf16x8 pa3) {
;   const s16x4 l0 = tr_read<v_rd_off(D0, 0, 0)>(vb), h0 = tr_read<v_rd_off(D0, 0, 1)>(vb), l1 = tr_read<v_rd_off(D0, 1, 0)>(vb), h1 = tr_read<v_rd_off(D0, 1, 1)>(vb);
;   const s16x4 l2 = tr_read<v_rd_off(D0, 2, 0)>(vb), h2 = tr_read<v_rd_off(D0, 2, 1)>(vb), l3 = tr_read<v_rd_off(D0, 3, 0)>(vb), h3 = tr_read<v_rd_off(D0, 3, 1)>(vb);
;   asm volatile("s_waitcnt lgkmcnt(0)" ::: "memory"); SBAR();
;     ...
;   od = __builtin_amdgcn_mfma_f32_32x32x16_bf16(pa0, PK(l0, h0), od, 0, 0, 0);
;   od = __builtin_amdgcn_mfma_f32_32x32x16_bf16(pa1, PK(l1, h1), od, 0, 0, 0);
;   od = __builtin_amdgcn_mfma_f32_32x32x16_bf16(pa2, PK(l2, h2), od, 0, 0, 0);
;   od = __builtin_amdgcn_mfma_f32_32x32x16_bf16(pa3, PK(l3, h3), od, 0, 0, 0);
;     ...
; }
; __device__ __forceinline__ void pv_d0(f32x16* o, int vb, bf16x8 pa0, bf16x8 pa1, bf16x8 pa2, bf16x8 pa3) {
;   pv_one<0>(o[0], vb, pa0, pa1, pa2, pa3); pv_one<1>(o[1], vb, pa0, pa1, pa2, pa3); pv_one<2>(o[2], vb, pa0, pa1, pa2, pa3); pv_one<3>(o[3], vb, pa0, pa1, pa2, pa3);
.Lda_skipk_1:
	s_barrier
	s_setprio 3
	s_waitcnt vmcnt(4)
	ds_write_b128 v197, v[134:137] offset:0
	ds_write_b128 v197, v[138:141] offset:8192
	ds_write_b128 v185, v[142:145] offset:0
	ds_write_b128 v185, v[146:149] offset:8192
	s_waitcnt lgkmcnt(10)
	v_mfma_f32_32x32x16_bf16 v[80:95], v[150:153], v[130:133], 0
	v_mfma_f32_32x32x16_bf16 v[64:79], v[154:157], v[130:133], 0
	global_load_dwordx4 v[134:137], v184, s[16:17]
	global_load_dwordx4 v[138:141], v184, s[2:3]
	global_load_dwordx4 v[142:145], v184, s[14:15]
	global_load_dwordx4 v[146:149], v184, s[10:11]
	s_add_u32 s16, s16, 0x60000
	s_addc_u32 s17, s17, 0
	s_add_u32 s2, s2, 0x60000
	s_addc_u32 s3, s3, 0
	s_add_u32 s14, s14, 0x60000
	s_addc_u32 s15, s15, 0
	s_add_u32 s10, s10, 0x60000
	s_addc_u32 s11, s11, 0
	ds_read_b128 v[150:153], v208 offset:32768
	ds_read_b128 v[154:157], v208 offset:40960
	s_waitcnt lgkmcnt(10)
	v_mfma_f32_32x32x16_bf16 v[80:95], v[158:161], v[126:129], v[80:95]
	v_mfma_f32_32x32x16_bf16 v[64:79], v[162:165], v[126:129], v[64:79]
	ds_read_b128 v[158:161], v209 offset:32768
	ds_read_b128 v[162:165], v209 offset:40960
	s_waitcnt lgkmcnt(10)
	v_mfma_f32_32x32x16_bf16 v[80:95], v[228:231], v[122:125], v[80:95]
	v_mfma_f32_32x32x16_bf16 v[64:79], v[232:235], v[122:125], v[64:79]
	ds_read_b128 v[228:231], v210 offset:32768
	ds_read_b128 v[232:235], v210 offset:40960
	s_waitcnt lgkmcnt(10)
	v_mfma_f32_32x32x16_bf16 v[80:95], v[236:239], v[118:121], v[80:95]
	v_mfma_f32_32x32x16_bf16 v[64:79], v[240:243], v[118:121], v[64:79]
	ds_read_b128 v[236:239], v211 offset:32768
	ds_read_b128 v[240:243], v211 offset:40960
	s_waitcnt lgkmcnt(6)
	v_mfma_f32_32x32x16_bf16 v[80:95], v[150:153], v[114:117], v[80:95]
	v_mfma_f32_32x32x16_bf16 v[64:79], v[154:157], v[114:117], v[64:79]
	ds_read_b64_tr_b16 v[150:151], v196 offset:16384
	ds_read_b64_tr_b16 v[152:153], v196 offset:18432
	ds_read_b64_tr_b16 v[154:155], v196 offset:20480
	ds_read_b64_tr_b16 v[156:157], v196 offset:22528
	s_waitcnt lgkmcnt(8)
	v_mfma_f32_32x32x16_bf16 v[80:95], v[158:161], v[110:113], v[80:95]
	v_mfma_f32_32x32x16_bf16 v[64:79], v[162:165], v[110:113], v[64:79]
	ds_read_b64_tr_b16 v[158:159], v196 offset:24576
	ds_read_b64_tr_b16 v[160:161], v196 offset:26624
	ds_read_b64_tr_b16 v[162:163], v196 offset:28672
	ds_read_b64_tr_b16 v[164:165], v196 offset:30720
	s_waitcnt lgkmcnt(10)
	v_mfma_f32_32x32x16_bf16 v[80:95], v[228:231], v[106:109], v[80:95]
	v_mfma_f32_32x32x16_bf16 v[64:79], v[232:235], v[106:109], v[64:79]
	ds_read_b64_tr_b16 v[228:229], v196 offset:16896
	ds_read_b64_tr_b16 v[230:231], v196 offset:18944
	ds_read_b64_tr_b16 v[232:233], v196 offset:20992
	ds_read_b64_tr_b16 v[234:235], v196 offset:23040
	s_waitcnt lgkmcnt(12)
	v_mfma_f32_32x32x16_bf16 v[80:95], v[236:239], v[102:105], v[80:95]
	v_mfma_f32_32x32x16_bf16 v[64:79], v[240:243], v[102:105], v[64:79]
	ds_read_b64_tr_b16 v[236:237], v196 offset:25088
	ds_read_b64_tr_b16 v[238:239], v196 offset:27136
	s_waitcnt lgkmcnt(12)
	v_mfma_f32_32x32x16_bf16 v[0:15], v[166:169], v[150:153], v[0:15]
	ds_read_b64_tr_b16 v[240:241], v196 offset:29184
	ds_read_b64_tr_b16 v[242:243], v196 offset:31232
	s_waitcnt lgkmcnt(12)
	v_mfma_f32_32x32x16_bf16 v[0:15], v[170:173], v[154:157], v[0:15]
	ds_read_b64_tr_b16 v[150:151], v196 offset:17408
	ds_read_b64_tr_b16 v[152:153], v196 offset:19456
	s_waitcnt lgkmcnt(12)
	v_mfma_f32_32x32x16_bf16 v[0:15], v[176:179], v[158:161], v[0:15]
	ds_read_b64_tr_b16 v[154:155], v196 offset:21504
	ds_read_b64_tr_b16 v[156:157], v196 offset:23552
	s_waitcnt lgkmcnt(12)
	v_mfma_f32_32x32x16_bf16 v[0:15], v[180:183], v[162:165], v[0:15]
	ds_read_b64_tr_b16 v[158:159], v196 offset:25600
	ds_read_b64_tr_b16 v[160:161], v196 offset:27648
	v_max3_f32 v190, v80, v81, v82
	v_max3_f32 v191, v64, v65, v66
	s_waitcnt lgkmcnt(12)
	v_mfma_f32_32x32x16_bf16 v[48:63], v[166:169], v[228:231], v[48:63]
	ds_read_b64_tr_b16 v[162:163], v196 offset:29696
	ds_read_b64_tr_b16 v[164:165], v196 offset:31744
	v_max3_f32 v190, v190, v83, v84
	v_max3_f32 v191, v191, v67, v68
	s_waitcnt lgkmcnt(12)
	v_mfma_f32_32x32x16_bf16 v[48:63], v[170:173], v[232:235], v[48:63]
	ds_read_b64_tr_b16 v[228:229], v196 offset:17920
	ds_read_b64_tr_b16 v[230:231], v196 offset:19968
	v_max3_f32 v190, v190, v85, v86
	v_max3_f32 v191, v191, v69, v70
	s_waitcnt lgkmcnt(12)
	v_mfma_f32_32x32x16_bf16 v[48:63], v[176:179], v[236:239], v[48:63]
	ds_read_b64_tr_b16 v[232:233], v196 offset:22016
	ds_read_b64_tr_b16 v[234:235], v196 offset:24064
	v_max3_f32 v190, v190, v87, v88
	v_max3_f32 v191, v191, v71, v72
	s_waitcnt lgkmcnt(12)
	v_mfma_f32_32x32x16_bf16 v[48:63], v[180:183], v[240:243], v[48:63]
	ds_read_b64_tr_b16 v[236:237], v196 offset:26112
	ds_read_b64_tr_b16 v[238:239], v196 offset:28160
	v_max3_f32 v190, v190, v89, v90
	v_max3_f32 v191, v191, v73, v74
	s_waitcnt lgkmcnt(12)
	v_mfma_f32_32x32x16_bf16 v[32:47], v[166:169], v[150:153], v[32:47]
	ds_read_b64_tr_b16 v[240:241], v196 offset:30208
	ds_read_b64_tr_b16 v[242:243], v196 offset:32256
	v_max3_f32 v190, v190, v91, v92
	v_max3_f32 v191, v191, v75, v76
	s_waitcnt lgkmcnt(12)
	v_mfma_f32_32x32x16_bf16 v[32:47], v[170:173], v[154:157], v[32:47]
	v_max3_f32 v190, v190, v93, v94
	v_max3_f32 v191, v191, v77, v78
	s_waitcnt lgkmcnt(10)
	v_mfma_f32_32x32x16_bf16 v[32:47], v[176:179], v[158:161], v[32:47]
	v_max3_f32 v190, v190, v95, v79
	v_max_f32_e32 v190, v190, v191
	s_waitcnt lgkmcnt(8)
	v_mfma_f32_32x32x16_bf16 v[32:47], v[180:183], v[162:165], v[32:47]
	v_mov_b32_e32 v191, v190
	s_nop 1
	v_permlane32_swap_b32_e32 v190, v191
	s_nop 0
	v_max_f32_e32 v212, v190, v191
	s_waitcnt lgkmcnt(6)
	v_mfma_f32_32x32x16_bf16 v[16:31], v[166:169], v[228:231], v[16:31]
	v_sub_f32_e32 v190, v212, v174
	v_cmp_ge_f32_e32 vcc, s86, v190
	v_max_f32_e32 v191, v174, v212
	v_sub_f32_e32 v215, v174, v191
	v_mul_f32_e32 v215, s92, v215
	s_waitcnt lgkmcnt(4)
	v_mfma_f32_32x32x16_bf16 v[16:31], v[170:173], v[232:235], v[16:31]
	s_nop 1
	s_cmp_eq_u64 vcc, exec
	s_cselect_b64 s[42:43], -1, 0
	s_waitcnt lgkmcnt(2)
	v_mfma_f32_32x32x16_bf16 v[16:31], v[176:179], v[236:239], v[16:31]
	v_exp_f32_e32 v213, v215
	s_nop 0
	v_cndmask_b32_e64 v174, v191, v174, s[42:43]
	s_waitcnt lgkmcnt(0)
	v_mfma_f32_32x32x16_bf16 v[16:31], v[180:183], v[240:243], v[16:31]
	v_cndmask_b32_e64 v213, v213, 1.0, s[42:43]
	v_mul_f32_e32 v214, 0xbe0293ee, v174
	s_setprio 0
	s_barrier
; __device__ __forceinline__ void partialSM(f32x16& p0, f32x16& p1, float& m_reg, float& mn, float& alpha) {
;     ...
;   float mnC = -mn * C;
; #pragma unroll
;   for (int r = 0; r < 16; ++r) p0[r] = fmaf(p0[r], C, mnC);
; #pragma unroll
;   for (int r = 0; r < 16; ++r) p1[r] = fmaf(p1[r], C, mnC);
; #pragma unroll
;   for (int r = 0; r < 16; ++r) p0[r] = __builtin_amdgcn_exp2f(p0[r]);
; }
; __device__ __forceinline__ void finishSM(f32x16& p0, f32x16& p1, float alpha, float& l_reg, bf16x8& pa0, bf16x8& pa1, bf16x8& pa2, bf16x8& pa3) {
; #pragma unroll
;   for (int r = 0; r < 16; ++r) p1[r] = __builtin_amdgcn_exp2f(p1[r]);
;   float ps = 0;
; #pragma unroll
;   for (int r = 0; r < 16; ++r) ps += p0[r];
; #pragma unroll
;   for (int r = 0; r < 16; ++r) ps += p1[r];
;   { auto rr = __builtin_amdgcn_permlane32_swap(__float_as_uint(ps), __float_as_uint(ps), false, false);
;     ps = __uint_as_float(rr[0]) + __uint_as_float(rr[1]); }
;   l_reg = l_reg * alpha + ps;
;     ...
;   PK4(p0, 0, pa0); PK4(p0, 8, pa1); PK4(p1, 0, pa2); PK4(p1, 8, pa3);
;     ...
; }
	v_cmp_gt_f32_e32 vcc, 1.0, v213
	v_fma_f32 v80, v80, s92, v214
	v_fma_f32 v81, v81, s92, v214
	v_fma_f32 v82, v82, s92, v214
	v_fma_f32 v83, v83, s92, v214
	v_fma_f32 v84, v84, s92, v214
	v_fma_f32 v85, v85, s92, v214
	v_fma_f32 v86, v86, s92, v214
	v_fma_f32 v87, v87, s92, v214
	v_fma_f32 v88, v88, s92, v214
	v_fma_f32 v89, v89, s92, v214
	v_fma_f32 v90, v90, s92, v214
	v_fma_f32 v91, v91, s92, v214
	v_fma_f32 v92, v92, s92, v214
	v_fma_f32 v93, v93, s92, v214
	v_fma_f32 v94, v94, s92, v214
	v_fma_f32 v95, v95, s92, v214
	v_fma_f32 v64, v64, s92, v214
	v_fma_f32 v65, v65, s92, v214
	v_fma_f32 v66, v66, s92, v214
	v_fma_f32 v67, v67, s92, v214
	v_fma_f32 v68, v68, s92, v214
	v_fma_f32 v69, v69, s92, v214
	v_fma_f32 v70, v70, s92, v214
	v_fma_f32 v71, v71, s92, v214
	v_fma_f32 v72, v72, s92, v214
	v_fma_f32 v73, v73, s92, v214
	v_fma_f32 v74, v74, s92, v214
	v_fma_f32 v75, v75, s92, v214
	v_fma_f32 v76, v76, s92, v214
	v_fma_f32 v77, v77, s92, v214
	v_fma_f32 v78, v78, s92, v214
	v_fma_f32 v79, v79, s92, v214
	s_cbranch_vccz .Lda_noresc_2
	s_and_saveexec_b64 s[12:13], s[40:41]
	ds_write_b32 v199, v213 offset:128
	s_or_b64 exec, exec, s[12:13]
	s_waitcnt lgkmcnt(0)
	v_add_u32_e32 v215, v99, v96
	ds_read_b128 v[228:231], v215 offset:128
	ds_read_b128 v[232:235], v215 offset:160
	ds_read_b128 v[236:239], v215 offset:192
	ds_read_b128 v[240:243], v215 offset:224
	s_waitcnt lgkmcnt(0)
	v_pk_mul_f32 v[0:1], v[0:1], v[228:229]
	v_pk_mul_f32 v[2:3], v[2:3], v[230:231]
	v_pk_mul_f32 v[4:5], v[4:5], v[232:233]
	v_pk_mul_f32 v[6:7], v[6:7], v[234:235]
	v_pk_mul_f32 v[8:9], v[8:9], v[236:237]
	v_pk_mul_f32 v[10:11], v[10:11], v[238:239]
	v_pk_mul_f32 v[12:13], v[12:13], v[240:241]
	v_pk_mul_f32 v[14:15], v[14:15], v[242:243]
	v_pk_mul_f32 v[48:49], v[48:49], v[228:229]
	v_pk_mul_f32 v[50:51], v[50:51], v[230:231]
	v_pk_mul_f32 v[52:53], v[52:53], v[232:233]
	v_pk_mul_f32 v[54:55], v[54:55], v[234:235]
	v_pk_mul_f32 v[56:57], v[56:57], v[236:237]
	v_pk_mul_f32 v[58:59], v[58:59], v[238:239]
	v_pk_mul_f32 v[60:61], v[60:61], v[240:241]
	v_pk_mul_f32 v[62:63], v[62:63], v[242:243]
	v_pk_mul_f32 v[32:33], v[32:33], v[228:229]
	v_pk_mul_f32 v[34:35], v[34:35], v[230:231]
	v_pk_mul_f32 v[36:37], v[36:37], v[232:233]
	v_pk_mul_f32 v[38:39], v[38:39], v[234:235]
	v_pk_mul_f32 v[40:41], v[40:41], v[236:237]
	v_pk_mul_f32 v[42:43], v[42:43], v[238:239]
	v_pk_mul_f32 v[44:45], v[44:45], v[240:241]
	v_pk_mul_f32 v[46:47], v[46:47], v[242:243]
	v_pk_mul_f32 v[16:17], v[16:17], v[228:229]
	v_pk_mul_f32 v[18:19], v[18:19], v[230:231]
	v_pk_mul_f32 v[20:21], v[20:21], v[232:233]
	v_pk_mul_f32 v[22:23], v[22:23], v[234:235]
	v_pk_mul_f32 v[24:25], v[24:25], v[236:237]
	v_pk_mul_f32 v[26:27], v[26:27], v[238:239]
	v_pk_mul_f32 v[28:29], v[28:29], v[240:241]
	v_pk_mul_f32 v[30:31], v[30:31], v[242:243]
.Lda_noresc_2:
	v_exp_f32_e32 v80, v80
	v_exp_f32_e32 v81, v81
	v_exp_f32_e32 v82, v82
	v_exp_f32_e32 v83, v83
	v_exp_f32_e32 v84, v84
	v_exp_f32_e32 v85, v85
	v_exp_f32_e32 v86, v86
	v_exp_f32_e32 v87, v87
	v_exp_f32_e32 v88, v88
	v_exp_f32_e32 v89, v89
	v_exp_f32_e32 v90, v90
	v_exp_f32_e32 v91, v91
	v_exp_f32_e32 v92, v92
	v_exp_f32_e32 v93, v93
	v_exp_f32_e32 v94, v94
	v_exp_f32_e32 v95, v95
	v_exp_f32_e32 v64, v64
	v_exp_f32_e32 v65, v65
	v_exp_f32_e32 v66, v66
	v_exp_f32_e32 v67, v67
	v_exp_f32_e32 v68, v68
	v_exp_f32_e32 v69, v69
	v_exp_f32_e32 v70, v70
	v_exp_f32_e32 v71, v71
	v_exp_f32_e32 v72, v72
	v_exp_f32_e32 v73, v73
	v_exp_f32_e32 v74, v74
	v_exp_f32_e32 v75, v75
	v_exp_f32_e32 v76, v76
	v_exp_f32_e32 v77, v77
	v_exp_f32_e32 v78, v78
	v_exp_f32_e32 v79, v79
	v_add_f32_e32 v190, v80, v81
	v_add_f32_e32 v191, v82, v83
	v_add_f32_e32 v190, v190, v84
	v_add_f32_e32 v191, v191, v85
	v_add_f32_e32 v190, v190, v86
	v_add_f32_e32 v191, v191, v87
	v_add_f32_e32 v190, v190, v88
	v_add_f32_e32 v191, v191, v89
	v_add_f32_e32 v190, v190, v90
	v_add_f32_e32 v191, v191, v91
	v_add_f32_e32 v190, v190, v92
	v_add_f32_e32 v191, v191, v93
	v_add_f32_e32 v190, v190, v94
	v_add_f32_e32 v191, v191, v95
	v_add_f32_e32 v190, v190, v64
	v_add_f32_e32 v191, v191, v65
	v_add_f32_e32 v190, v190, v66
	v_add_f32_e32 v191, v191, v67
	v_add_f32_e32 v190, v190, v68
	v_add_f32_e32 v191, v191, v69
	v_add_f32_e32 v190, v190, v70
	v_add_f32_e32 v191, v191, v71
	v_add_f32_e32 v190, v190, v72
	v_add_f32_e32 v191, v191, v73
	v_add_f32_e32 v190, v190, v74
	v_add_f32_e32 v191, v191, v75
	v_add_f32_e32 v190, v190, v76
	v_add_f32_e32 v191, v191, v77
	v_add_f32_e32 v190, v190, v78
	v_add_f32_e32 v191, v191, v79
	v_add_f32_e32 v190, v190, v191
	v_mov_b32_e32 v191, v190
	v_cvt_pk_bf16_f32 v166, v80, v81
	v_cvt_pk_bf16_f32 v167, v82, v83
	v_cvt_pk_bf16_f32 v168, v84, v85
	v_cvt_pk_bf16_f32 v169, v86, v87
	v_cvt_pk_bf16_f32 v170, v88, v89
	v_cvt_pk_bf16_f32 v171, v90, v91
	v_cvt_pk_bf16_f32 v172, v92, v93
	v_cvt_pk_bf16_f32 v173, v94, v95
	v_cvt_pk_bf16_f32 v176, v64, v65
	v_cvt_pk_bf16_f32 v177, v66, v67
	v_cvt_pk_bf16_f32 v178, v68, v69
	v_cvt_pk_bf16_f32 v179, v70, v71
	v_cvt_pk_bf16_f32 v180, v72, v73
	v_cvt_pk_bf16_f32 v181, v74, v75
	v_cvt_pk_bf16_f32 v182, v76, v77
	v_cvt_pk_bf16_f32 v183, v78, v79
	s_nop 1
	v_permlane32_swap_b32_e32 v190, v191
	v_permlane32_swap_b32_e32 v166, v168
	v_permlane32_swap_b32_e32 v167, v169
	v_permlane32_swap_b32_e32 v170, v172
	v_permlane32_swap_b32_e32 v171, v173
	v_permlane32_swap_b32_e32 v176, v178
	v_permlane32_swap_b32_e32 v177, v179
	v_permlane32_swap_b32_e32 v180, v182
	v_permlane32_swap_b32_e32 v181, v183
	v_add_f32_e32 v190, v190, v191
	v_fma_f32 v175, v175, v213, v190
	s_add_u32 s31, s31, 1
	s_cmp_lt_u32 s31, 132
	s_cbranch_scc0 .Lda_skipk_2
	ds_read_b128 v[150:153], v204 offset:49152
	ds_read_b128 v[154:157], v204 offset:57344
	ds_read_b128 v[158:161], v205 offset:49152
	ds_read_b128 v[162:165], v205 offset:57344
	ds_read_b128 v[228:231], v206 offset:49152
	ds_read_b128 v[232:235], v206 offset:57344
	ds_read_b128 v[236:239], v207 offset:49152
	ds_read_b128 v[240:243], v207 offset:57344
; __device__ __forceinline__ void partialSM(f32x16& p0, f32x16& p1, float& m_reg, float& mn, float& alpha) {
; __device__ __forceinline__ void qkt(f32x16& p0, f32x16& p1, const bf16_t* Ks, const bf16x8* qr, int r32, int hi) {
;   p0 = f32x16{}; p1 = f32x16{};
; #pragma unroll
;   for (int d0 = 0; d0 < 8; ++d0) { int cb = (d0 * 16 + hi * 8) * 2;
;     bf16x8 b0 = *reinterpret_cast<const bf16x8*>((const char*)Ks + KSWZ(r32, cb));
;     bf16x8 b1 = *reinterpret_cast<const bf16x8*>((const char*)Ks + KSWZ(32 + r32, cb));
;     p0 = __builtin_amdgcn_mfma_f32_32x32x16_bf16(b0, qr[d0], p0, 0, 0, 0);
;     p1 = __builtin_amdgcn_mfma_f32_32x32x16_bf16(b1, qr[d0], p1, 0, 0, 0); }
; }
; __device__ __forceinline__ int v_st(int k, int c) { const int kk = (k & ~0xC) | ((k & 4) << 1) | ((k & 8) >> 1); return ((kk >> 3) * 4 + (c >> 5)) * 512 + ((kk & 7) * 32 + (c & 31)) * 2; }
; __device__ __forceinline__ int v_rd_base(int lane) { return ((lane & 3) << 3) | (((lane >> 2) & 3) << 6) | (((lane >> 4) & 1) << 5) | (((lane >> 5) & 1) << 8); }
; template <int OFF> __device__ __forceinline__ s16x4 tr_read(int vb) {
;   s16x4 r; asm volatile("ds_read_b64_tr_b16 %0, %1 offset:%2" : "=&v"(r) : "v"(vb), "i"(OFF) : "memory"); return r;
; }
; template <int D0> __device__ __forceinline__ void pv_one(f32x16& od, int vb, bf16x8 pa0, bf16x8 pa1, bf16x8 pa2, bf16x8 pa3) {
;   const s16x4 l0 = tr_read<v_rd_off(D0, 0, 0)>(vb), h0 = tr_read<v_rd_off(D0, 0, 1)>(vb), l1 = tr_read<v_rd_off(D0, 1, 0)>(vb), h1 = tr_read<v_rd_off(D0, 1, 1)>(vb);
;   const s16x4 l2 = tr_read<v_rd_off(D0, 2, 0)>(vb), h2 = tr_read<v_rd_off(D0, 2, 1)>(vb), l3 = tr_read<v_rd_off(D0, 3, 0)>(vb), h3 = tr_read<v_rd_off(D0, 3, 1)>(vb);
;   asm volatile("s_waitcnt lgkmcnt(0)" ::: "memory"); SBAR();
;     ...
;   od = __builtin_amdgcn_mfma_f32_32x32x16_bf16(pa0, PK(l0, h0), od, 0, 0, 0);
;   od = __builtin_amdgcn_mfma_f32_32x32x16_bf16(pa1, PK(l1, h1), od, 0, 0, 0);
;   od = __builtin_amdgcn_mfma_f32_32x32x16_bf16(pa2, PK(l2, h2), od, 0, 0, 0);
;   od = __builtin_amdgcn_mfma_f32_32x32x16_bf16(pa3, PK(l3, h3), od, 0, 0, 0);
;     ...
; }
; __device__ __forceinline__ void pv_d0(f32x16* o, int vb, bf16x8 pa0, bf16x8 pa1, bf16x8 pa2, bf16x8 pa3) {
;   pv_one<0>(o[0], vb, pa0, pa1, pa2, pa3); pv_one<1>(o[1], vb, pa0, pa1, pa2, pa3); pv_one<2>(o[2], vb, pa0, pa1, pa2, pa3); pv_one<3>(o[3], vb, pa0, pa1, pa2, pa3);
.Lda_skipk_2:
	s_barrier
	s_setprio 3
	s_waitcnt vmcnt(4)
	ds_write_b128 v197, v[186:189] offset:16384
	ds_write_b128 v197, v[220:223] offset:24576
	ds_write_b128 v185, v[246:249] offset:16384
	ds_write_b128 v185, v[200:203] offset:24576
	s_waitcnt lgkmcnt(10)
	v_mfma_f32_32x32x16_bf16 v[80:95], v[150:153], v[130:133], 0
	v_mfma_f32_32x32x16_bf16 v[64:79], v[154:157], v[130:133], 0
	global_load_dwordx4 v[186:189], v184, s[16:17]
	global_load_dwordx4 v[220:223], v184, s[2:3]
	global_load_dwordx4 v[246:249], v184, s[14:15]
	global_load_dwordx4 v[200:203], v184, s[10:11]
	s_add_u32 s16, s16, 0x60000
	s_addc_u32 s17, s17, 0
	s_add_u32 s2, s2, 0x60000
	s_addc_u32 s3, s3, 0
	s_add_u32 s14, s14, 0x60000
	s_addc_u32 s15, s15, 0
	s_add_u32 s10, s10, 0x60000
	s_addc_u32 s11, s11, 0
	ds_read_b128 v[150:153], v208 offset:49152
	ds_read_b128 v[154:157], v208 offset:57344
	s_waitcnt lgkmcnt(10)
	v_mfma_f32_32x32x16_bf16 v[80:95], v[158:161], v[126:129], v[80:95]
	v_mfma_f32_32x32x16_bf16 v[64:79], v[162:165], v[126:129], v[64:79]
	ds_read_b128 v[158:161], v209 offset:49152
	ds_read_b128 v[162:165], v209 offset:57344
	s_waitcnt lgkmcnt(10)
	v_mfma_f32_32x32x16_bf16 v[80:95], v[228:231], v[122:125], v[80:95]
	v_mfma_f32_32x32x16_bf16 v[64:79], v[232:235], v[122:125], v[64:79]
	ds_read_b128 v[228:231], v210 offset:49152
	ds_read_b128 v[232:235], v210 offset:57344
	s_waitcnt lgkmcnt(10)
	v_mfma_f32_32x32x16_bf16 v[80:95], v[236:239], v[118:121], v[80:95]
	v_mfma_f32_32x32x16_bf16 v[64:79], v[240:243], v[118:121], v[64:79]
	ds_read_b128 v[236:239], v211 offset:49152
	ds_read_b128 v[240:243], v211 offset:57344
	s_waitcnt lgkmcnt(6)
	v_mfma_f32_32x32x16_bf16 v[80:95], v[150:153], v[114:117], v[80:95]
	v_mfma_f32_32x32x16_bf16 v[64:79], v[154:157], v[114:117], v[64:79]
	ds_read_b64_tr_b16 v[150:151], v196 offset:32768
	ds_read_b64_tr_b16 v[152:153], v196 offset:34816
	ds_read_b64_tr_b16 v[154:155], v196 offset:36864
	ds_read_b64_tr_b16 v[156:157], v196 offset:38912
	s_waitcnt lgkmcnt(8)
	v_mfma_f32_32x32x16_bf16 v[80:95], v[158:161], v[110:113], v[80:95]
	v_mfma_f32_32x32x16_bf16 v[64:79], v[162:165], v[110:113], v[64:79]
	ds_read_b64_tr_b16 v[158:159], v196 offset:40960
	ds_read_b64_tr_b16 v[160:161], v196 offset:43008
	ds_read_b64_tr_b16 v[162:163], v196 offset:45056
	ds_read_b64_tr_b16 v[164:165], v196 offset:47104
	s_waitcnt lgkmcnt(10)
	v_mfma_f32_32x32x16_bf16 v[80:95], v[228:231], v[106:109], v[80:95]
	v_mfma_f32_32x32x16_bf16 v[64:79], v[232:235], v[106:109], v[64:79]
	ds_read_b64_tr_b16 v[228:229], v196 offset:33280
	ds_read_b64_tr_b16 v[230:231], v196 offset:35328
	ds_read_b64_tr_b16 v[232:233], v196 offset:37376
	ds_read_b64_tr_b16 v[234:235], v196 offset:39424
	s_waitcnt lgkmcnt(12)
	v_mfma_f32_32x32x16_bf16 v[80:95], v[236:239], v[102:105], v[80:95]
	v_mfma_f32_32x32x16_bf16 v[64:79], v[240:243], v[102:105], v[64:79]
	ds_read_b64_tr_b16 v[236:237], v196 offset:41472
	ds_read_b64_tr_b16 v[238:239], v196 offset:43520
	s_waitcnt lgkmcnt(12)
	v_mfma_f32_32x32x16_bf16 v[0:15], v[166:169], v[150:153], v[0:15]
	ds_read_b64_tr_b16 v[240:241], v196 offset:45568
	ds_read_b64_tr_b16 v[242:243], v196 offset:47616
	s_waitcnt lgkmcnt(12)
	v_mfma_f32_32x32x16_bf16 v[0:15], v[170:173], v[154:157], v[0:15]
	ds_read_b64_tr_b16 v[150:151], v196 offset:33792
	ds_read_b64_tr_b16 v[152:153], v196 offset:35840
	s_waitcnt lgkmcnt(12)
	v_mfma_f32_32x32x16_bf16 v[0:15], v[176:179], v[158:161], v[0:15]
	ds_read_b64_tr_b16 v[154:155], v196 offset:37888
	ds_read_b64_tr_b16 v[156:157], v196 offset:39936
	s_waitcnt lgkmcnt(12)
	v_mfma_f32_32x32x16_bf16 v[0:15], v[180:183], v[162:165], v[0:15]
	ds_read_b64_tr_b16 v[158:159], v196 offset:41984
	ds_read_b64_tr_b16 v[160:161], v196 offset:44032
	v_max3_f32 v190, v80, v81, v82
	v_max3_f32 v191, v64, v65, v66
	s_waitcnt lgkmcnt(12)
	v_mfma_f32_32x32x16_bf16 v[48:63], v[166:169], v[228:231], v[48:63]
	ds_read_b64_tr_b16 v[162:163], v196 offset:46080
	ds_read_b64_tr_b16 v[164:165], v196 offset:48128
	v_max3_f32 v190, v190, v83, v84
	v_max3_f32 v191, v191, v67, v68
	s_waitcnt lgkmcnt(12)
	v_mfma_f32_32x32x16_bf16 v[48:63], v[170:173], v[232:235], v[48:63]
	ds_read_b64_tr_b16 v[228:229], v196 offset:34304
	ds_read_b64_tr_b16 v[230:231], v196 offset:36352
	v_max3_f32 v190, v190, v85, v86
	v_max3_f32 v191, v191, v69, v70
	s_waitcnt lgkmcnt(12)
	v_mfma_f32_32x32x16_bf16 v[48:63], v[176:179], v[236:239], v[48:63]
	ds_read_b64_tr_b16 v[232:233], v196 offset:38400
	ds_read_b64_tr_b16 v[234:235], v196 offset:40448
	v_max3_f32 v190, v190, v87, v88
	v_max3_f32 v191, v191, v71, v72
	s_waitcnt lgkmcnt(12)
	v_mfma_f32_32x32x16_bf16 v[48:63], v[180:183], v[240:243], v[48:63]
	ds_read_b64_tr_b16 v[236:237], v196 offset:42496
	ds_read_b64_tr_b16 v[238:239], v196 offset:44544
	v_max3_f32 v190, v190, v89, v90
	v_max3_f32 v191, v191, v73, v74
	s_waitcnt lgkmcnt(12)
	v_mfma_f32_32x32x16_bf16 v[32:47], v[166:169], v[150:153], v[32:47]
	ds_read_b64_tr_b16 v[240:241], v196 offset:46592
	ds_read_b64_tr_b16 v[242:243], v196 offset:48640
	v_max3_f32 v190, v190, v91, v92
	v_max3_f32 v191, v191, v75, v76
	s_waitcnt lgkmcnt(12)
	v_mfma_f32_32x32x16_bf16 v[32:47], v[170:173], v[154:157], v[32:47]
	v_max3_f32 v190, v190, v93, v94
	v_max3_f32 v191, v191, v77, v78
	s_waitcnt lgkmcnt(10)
	v_mfma_f32_32x32x16_bf16 v[32:47], v[176:179], v[158:161], v[32:47]
	v_max3_f32 v190, v190, v95, v79
	v_max_f32_e32 v190, v190, v191
	s_waitcnt lgkmcnt(8)
	v_mfma_f32_32x32x16_bf16 v[32:47], v[180:183], v[162:165], v[32:47]
	v_mov_b32_e32 v191, v190
	s_nop 1
	v_permlane32_swap_b32_e32 v190, v191
	s_nop 0
	v_max_f32_e32 v212, v190, v191
	s_waitcnt lgkmcnt(6)
	v_mfma_f32_32x32x16_bf16 v[16:31], v[166:169], v[228:231], v[16:31]
	v_sub_f32_e32 v190, v212, v174
	v_cmp_ge_f32_e32 vcc, s86, v190
	v_max_f32_e32 v191, v174, v212
	v_sub_f32_e32 v215, v174, v191
	v_mul_f32_e32 v215, s92, v215
	s_waitcnt lgkmcnt(4)
	v_mfma_f32_32x32x16_bf16 v[16:31], v[170:173], v[232:235], v[16:31]
	s_nop 1
	s_cmp_eq_u64 vcc, exec
	s_cselect_b64 s[42:43], -1, 0
	s_waitcnt lgkmcnt(2)
	v_mfma_f32_32x32x16_bf16 v[16:31], v[176:179], v[236:239], v[16:31]
	v_exp_f32_e32 v213, v215
	s_nop 0
	v_cndmask_b32_e64 v174, v191, v174, s[42:43]
	s_waitcnt lgkmcnt(0)
	v_mfma_f32_32x32x16_bf16 v[16:31], v[180:183], v[240:243], v[16:31]
	v_cndmask_b32_e64 v213, v213, 1.0, s[42:43]
	v_mul_f32_e32 v214, 0xbe0293ee, v174
	s_setprio 0
	s_barrier
; __device__ __forceinline__ void partialSM(f32x16& p0, f32x16& p1, float& m_reg, float& mn, float& alpha) {
;     ...
;   float mnC = -mn * C;
; #pragma unroll
;   for (int r = 0; r < 16; ++r) p0[r] = fmaf(p0[r], C, mnC);
; #pragma unroll
;   for (int r = 0; r < 16; ++r) p1[r] = fmaf(p1[r], C, mnC);
; #pragma unroll
;   for (int r = 0; r < 16; ++r) p0[r] = __builtin_amdgcn_exp2f(p0[r]);
; }
; __device__ __forceinline__ void finishSM(f32x16& p0, f32x16& p1, float alpha, float& l_reg, bf16x8& pa0, bf16x8& pa1, bf16x8& pa2, bf16x8& pa3) {
; #pragma unroll
;   for (int r = 0; r < 16; ++r) p1[r] = __builtin_amdgcn_exp2f(p1[r]);
;   float ps = 0;
; #pragma unroll
;   for (int r = 0; r < 16; ++r) ps += p0[r];
; #pragma unroll
;   for (int r = 0; r < 16; ++r) ps += p1[r];
;   { auto rr = __builtin_amdgcn_permlane32_swap(__float_as_uint(ps), __float_as_uint(ps), false, false);
;     ps = __uint_as_float(rr[0]) + __uint_as_float(rr[1]); }
;   l_reg = l_reg * alpha + ps;
;     ...
;   PK4(p0, 0, pa0); PK4(p0, 8, pa1); PK4(p1, 0, pa2); PK4(p1, 8, pa3);
;     ...
; }
	v_cmp_gt_f32_e32 vcc, 1.0, v213
	v_fma_f32 v80, v80, s92, v214
	v_fma_f32 v81, v81, s92, v214
	v_fma_f32 v82, v82, s92, v214
	v_fma_f32 v83, v83, s92, v214
	v_fma_f32 v84, v84, s92, v214
	v_fma_f32 v85, v85, s92, v214
	v_fma_f32 v86, v86, s92, v214
	v_fma_f32 v87, v87, s92, v214
	v_fma_f32 v88, v88, s92, v214
	v_fma_f32 v89, v89, s92, v214
	v_fma_f32 v90, v90, s92, v214
	v_fma_f32 v91, v91, s92, v214
	v_fma_f32 v92, v92, s92, v214
	v_fma_f32 v93, v93, s92, v214
	v_fma_f32 v94, v94, s92, v214
	v_fma_f32 v95, v95, s92, v214
	v_fma_f32 v64, v64, s92, v214
	v_fma_f32 v65, v65, s92, v214
	v_fma_f32 v66, v66, s92, v214
	v_fma_f32 v67, v67, s92, v214
	v_fma_f32 v68, v68, s92, v214
	v_fma_f32 v69, v69, s92, v214
	v_fma_f32 v70, v70, s92, v214
	v_fma_f32 v71, v71, s92, v214
	v_fma_f32 v72, v72, s92, v214
	v_fma_f32 v73, v73, s92, v214
	v_fma_f32 v74, v74, s92, v214
	v_fma_f32 v75, v75, s92, v214
	v_fma_f32 v76, v76, s92, v214
	v_fma_f32 v77, v77, s92, v214
	v_fma_f32 v78, v78, s92, v214
	v_fma_f32 v79, v79, s92, v214
	s_cbranch_vccz .Lda_noresc_3
	s_and_saveexec_b64 s[12:13], s[40:41]
	ds_write_b32 v199, v213 offset:128
	s_or_b64 exec, exec, s[12:13]
	s_waitcnt lgkmcnt(0)
	v_add_u32_e32 v215, v99, v96
	ds_read_b128 v[228:231], v215 offset:128
	ds_read_b128 v[232:235], v215 offset:160
	ds_read_b128 v[236:239], v215 offset:192
	ds_read_b128 v[240:243], v215 offset:224
	s_waitcnt lgkmcnt(0)
	v_pk_mul_f32 v[0:1], v[0:1], v[228:229]
	v_pk_mul_f32 v[2:3], v[2:3], v[230:231]
	v_pk_mul_f32 v[4:5], v[4:5], v[232:233]
	v_pk_mul_f32 v[6:7], v[6:7], v[234:235]
	v_pk_mul_f32 v[8:9], v[8:9], v[236:237]
	v_pk_mul_f32 v[10:11], v[10:11], v[238:239]
	v_pk_mul_f32 v[12:13], v[12:13], v[240:241]
	v_pk_mul_f32 v[14:15], v[14:15], v[242:243]
	v_pk_mul_f32 v[48:49], v[48:49], v[228:229]
	v_pk_mul_f32 v[50:51], v[50:51], v[230:231]
	v_pk_mul_f32 v[52:53], v[52:53], v[232:233]
	v_pk_mul_f32 v[54:55], v[54:55], v[234:235]
	v_pk_mul_f32 v[56:57], v[56:57], v[236:237]
	v_pk_mul_f32 v[58:59], v[58:59], v[238:239]
	v_pk_mul_f32 v[60:61], v[60:61], v[240:241]
	v_pk_mul_f32 v[62:63], v[62:63], v[242:243]
	v_pk_mul_f32 v[32:33], v[32:33], v[228:229]
	v_pk_mul_f32 v[34:35], v[34:35], v[230:231]
	v_pk_mul_f32 v[36:37], v[36:37], v[232:233]
	v_pk_mul_f32 v[38:39], v[38:39], v[234:235]
	v_pk_mul_f32 v[40:41], v[40:41], v[236:237]
	v_pk_mul_f32 v[42:43], v[42:43], v[238:239]
	v_pk_mul_f32 v[44:45], v[44:45], v[240:241]
	v_pk_mul_f32 v[46:47], v[46:47], v[242:243]
	v_pk_mul_f32 v[16:17], v[16:17], v[228:229]
	v_pk_mul_f32 v[18:19], v[18:19], v[230:231]
	v_pk_mul_f32 v[20:21], v[20:21], v[232:233]
	v_pk_mul_f32 v[22:23], v[22:23], v[234:235]
	v_pk_mul_f32 v[24:25], v[24:25], v[236:237]
	v_pk_mul_f32 v[26:27], v[26:27], v[238:239]
	v_pk_mul_f32 v[28:29], v[28:29], v[240:241]
	v_pk_mul_f32 v[30:31], v[30:31], v[242:243]
.Lda_noresc_3:
	v_exp_f32_e32 v80, v80
	v_exp_f32_e32 v81, v81
	v_exp_f32_e32 v82, v82
	v_exp_f32_e32 v83, v83
	v_exp_f32_e32 v84, v84
	v_exp_f32_e32 v85, v85
	v_exp_f32_e32 v86, v86
	v_exp_f32_e32 v87, v87
	v_exp_f32_e32 v88, v88
	v_exp_f32_e32 v89, v89
	v_exp_f32_e32 v90, v90
	v_exp_f32_e32 v91, v91
	v_exp_f32_e32 v92, v92
	v_exp_f32_e32 v93, v93
	v_exp_f32_e32 v94, v94
	v_exp_f32_e32 v95, v95
	v_exp_f32_e32 v64, v64
	v_exp_f32_e32 v65, v65
	v_exp_f32_e32 v66, v66
	v_exp_f32_e32 v67, v67
	v_exp_f32_e32 v68, v68
	v_exp_f32_e32 v69, v69
	v_exp_f32_e32 v70, v70
	v_exp_f32_e32 v71, v71
	v_exp_f32_e32 v72, v72
	v_exp_f32_e32 v73, v73
	v_exp_f32_e32 v74, v74
	v_exp_f32_e32 v75, v75
	v_exp_f32_e32 v76, v76
	v_exp_f32_e32 v77, v77
	v_exp_f32_e32 v78, v78
	v_exp_f32_e32 v79, v79
	v_add_f32_e32 v190, v80, v81
	v_add_f32_e32 v191, v82, v83
	v_add_f32_e32 v190, v190, v84
	v_add_f32_e32 v191, v191, v85
	v_add_f32_e32 v190, v190, v86
	v_add_f32_e32 v191, v191, v87
	v_add_f32_e32 v190, v190, v88
	v_add_f32_e32 v191, v191, v89
	v_add_f32_e32 v190, v190, v90
	v_add_f32_e32 v191, v191, v91
	v_add_f32_e32 v190, v190, v92
	v_add_f32_e32 v191, v191, v93
	v_add_f32_e32 v190, v190, v94
	v_add_f32_e32 v191, v191, v95
	v_add_f32_e32 v190, v190, v64
	v_add_f32_e32 v191, v191, v65
	v_add_f32_e32 v190, v190, v66
	v_add_f32_e32 v191, v191, v67
	v_add_f32_e32 v190, v190, v68
	v_add_f32_e32 v191, v191, v69
	v_add_f32_e32 v190, v190, v70
	v_add_f32_e32 v191, v191, v71
	v_add_f32_e32 v190, v190, v72
	v_add_f32_e32 v191, v191, v73
	v_add_f32_e32 v190, v190, v74
	v_add_f32_e32 v191, v191, v75
	v_add_f32_e32 v190, v190, v76
	v_add_f32_e32 v191, v191, v77
	v_add_f32_e32 v190, v190, v78
	v_add_f32_e32 v191, v191, v79
	v_add_f32_e32 v190, v190, v191
	v_mov_b32_e32 v191, v190
	v_cvt_pk_bf16_f32 v166, v80, v81
	v_cvt_pk_bf16_f32 v167, v82, v83
	v_cvt_pk_bf16_f32 v168, v84, v85
	v_cvt_pk_bf16_f32 v169, v86, v87
	v_cvt_pk_bf16_f32 v170, v88, v89
	v_cvt_pk_bf16_f32 v171, v90, v91
	v_cvt_pk_bf16_f32 v172, v92, v93
	v_cvt_pk_bf16_f32 v173, v94, v95
	v_cvt_pk_bf16_f32 v176, v64, v65
	v_cvt_pk_bf16_f32 v177, v66, v67
	v_cvt_pk_bf16_f32 v178, v68, v69
	v_cvt_pk_bf16_f32 v179, v70, v71
	v_cvt_pk_bf16_f32 v180, v72, v73
	v_cvt_pk_bf16_f32 v181, v74, v75
	v_cvt_pk_bf16_f32 v182, v76, v77
	v_cvt_pk_bf16_f32 v183, v78, v79
	s_nop 1
	v_permlane32_swap_b32_e32 v190, v191
	v_permlane32_swap_b32_e32 v166, v168
	v_permlane32_swap_b32_e32 v167, v169
	v_permlane32_swap_b32_e32 v170, v172
	v_permlane32_swap_b32_e32 v171, v173
	v_permlane32_swap_b32_e32 v176, v178
	v_permlane32_swap_b32_e32 v177, v179
	v_permlane32_swap_b32_e32 v180, v182
	v_permlane32_swap_b32_e32 v181, v183
	v_add_f32_e32 v190, v190, v191
	v_fma_f32 v175, v175, v213, v190
	s_add_u32 s31, s31, 1
	s_cmp_lt_u32 s31, 132
	s_cbranch_scc0 .Lda_skipk_3
	ds_read_b128 v[150:153], v204 offset:0
	ds_read_b128 v[154:157], v204 offset:8192
	ds_read_b128 v[158:161], v205 offset:0
	ds_read_b128 v[162:165], v205 offset:8192
	ds_read_b128 v[228:231], v206 offset:0
	ds_read_b128 v[232:235], v206 offset:8192
	ds_read_b128 v[236:239], v207 offset:0
	ds_read_b128 v[240:243], v207 offset:8192
; #define SBAR() __builtin_amdgcn_sched_barrier(0)
; #define RESC(a) do { if (__any((a) < 1.f)) { if (hi == 0) al_l[r32] = (a); asm volatile("s_waitcnt lgkmcnt(0)" ::: "memory"); \
;     _Pragma("unroll") for (int d = 0; d < 4; ++d) _Pragma("unroll") for (int r = 0; r < 16; ++r) o[d][r] *= al_l[crow(r, hi)]; } } while (0)
; template <int MODE, int SDEPTH>
; __device__ __forceinline__ void attn_unit(const UnitP& u, char* lds) {
;     ...
;   SBAR(); qkt(pB0, pB1, (bf16_t*)((char*)K_lds + SHM_K), qr, r32, hi);
;   finishSM(pA0, pA1, alA, l_reg, pa0, pa1, pa2, pa3); SBAR();
;   pv_d0(o, vb0, pa0, pa1, pa2, pa3); mask_tile<MODE>(pB0, pB1, u, NT - 1, wid, r32, hi, biasL); partialSM(pB0, pB1, m_reg, mnB, alB);
;   __syncthreads(); RESC(alB);
;   finishSM(pB0, pB1, alB, l_reg, pa0, pa1, pa2, pa3); SBAR();
;   pv_d0(o, vb0 + (int)SHM_V, pa0, pa1, pa2, pa3);
.Lda_skipk_3:
	s_barrier
	s_cmp_lt_u32 s31, 132
	s_cbranch_scc1 .Lda_loop
	s_setprio 3
	ds_read_b64_tr_b16 v[150:151], v196 offset:49152
	ds_read_b64_tr_b16 v[152:153], v196 offset:51200
	ds_read_b64_tr_b16 v[154:155], v196 offset:53248
	ds_read_b64_tr_b16 v[156:157], v196 offset:55296
	ds_read_b64_tr_b16 v[158:159], v196 offset:57344
	ds_read_b64_tr_b16 v[160:161], v196 offset:59392
	ds_read_b64_tr_b16 v[162:163], v196 offset:61440
	ds_read_b64_tr_b16 v[164:165], v196 offset:63488
	ds_read_b64_tr_b16 v[228:229], v196 offset:49664
	ds_read_b64_tr_b16 v[230:231], v196 offset:51712
	ds_read_b64_tr_b16 v[232:233], v196 offset:53760
	ds_read_b64_tr_b16 v[234:235], v196 offset:55808
	ds_read_b64_tr_b16 v[236:237], v196 offset:57856
	ds_read_b64_tr_b16 v[238:239], v196 offset:59904
	s_waitcnt lgkmcnt(12)
	v_mfma_f32_32x32x16_bf16 v[0:15], v[166:169], v[150:153], v[0:15]
	ds_read_b64_tr_b16 v[240:241], v196 offset:61952
	ds_read_b64_tr_b16 v[242:243], v196 offset:64000
	s_waitcnt lgkmcnt(12)
	v_mfma_f32_32x32x16_bf16 v[0:15], v[170:173], v[154:157], v[0:15]
	ds_read_b64_tr_b16 v[150:151], v196 offset:50176
	ds_read_b64_tr_b16 v[152:153], v196 offset:52224
	s_waitcnt lgkmcnt(12)
	v_mfma_f32_32x32x16_bf16 v[0:15], v[176:179], v[158:161], v[0:15]
	ds_read_b64_tr_b16 v[154:155], v196 offset:54272
	ds_read_b64_tr_b16 v[156:157], v196 offset:56320
	s_waitcnt lgkmcnt(12)
	v_mfma_f32_32x32x16_bf16 v[0:15], v[180:183], v[162:165], v[0:15]
	ds_read_b64_tr_b16 v[158:159], v196 offset:58368
	ds_read_b64_tr_b16 v[160:161], v196 offset:60416
	s_waitcnt lgkmcnt(12)
	v_mfma_f32_32x32x16_bf16 v[48:63], v[166:169], v[228:231], v[48:63]
	ds_read_b64_tr_b16 v[162:163], v196 offset:62464
	ds_read_b64_tr_b16 v[164:165], v196 offset:64512
	s_waitcnt lgkmcnt(12)
	v_mfma_f32_32x32x16_bf16 v[48:63], v[170:173], v[232:235], v[48:63]
	ds_read_b64_tr_b16 v[228:229], v196 offset:50688
	ds_read_b64_tr_b16 v[230:231], v196 offset:52736
	s_waitcnt lgkmcnt(12)
	v_mfma_f32_32x32x16_bf16 v[48:63], v[176:179], v[236:239], v[48:63]
	ds_read_b64_tr_b16 v[232:233], v196 offset:54784
	ds_read_b64_tr_b16 v[234:235], v196 offset:56832
	s_waitcnt lgkmcnt(12)
	v_mfma_f32_32x32x16_bf16 v[48:63], v[180:183], v[240:243], v[48:63]
	ds_read_b64_tr_b16 v[236:237], v196 offset:58880
	ds_read_b64_tr_b16 v[238:239], v196 offset:60928
	s_waitcnt lgkmcnt(12)
	v_mfma_f32_32x32x16_bf16 v[32:47], v[166:169], v[150:153], v[32:47]
	ds_read_b64_tr_b16 v[240:241], v196 offset:62976
	ds_read_b64_tr_b16 v[242:243], v196 offset:65024
	s_waitcnt lgkmcnt(12)
	v_mfma_f32_32x32x16_bf16 v[32:47], v[170:173], v[154:157], v[32:47]
	s_waitcnt lgkmcnt(10)
	v_mfma_f32_32x32x16_bf16 v[32:47], v[176:179], v[158:161], v[32:47]
	s_waitcnt lgkmcnt(8)
	v_mfma_f32_32x32x16_bf16 v[32:47], v[180:183], v[162:165], v[32:47]
	s_waitcnt lgkmcnt(6)
	v_mfma_f32_32x32x16_bf16 v[16:31], v[166:169], v[228:231], v[16:31]
	s_waitcnt lgkmcnt(4)
	v_mfma_f32_32x32x16_bf16 v[16:31], v[170:173], v[232:235], v[16:31]
	s_waitcnt lgkmcnt(2)
	v_mfma_f32_32x32x16_bf16 v[16:31], v[176:179], v[236:239], v[16:31]
	s_waitcnt lgkmcnt(0)
	v_mfma_f32_32x32x16_bf16 v[16:31], v[180:183], v[240:243], v[16:31]
	s_nop 12
	s_setprio 0
	s_cmp_lt_u32 s36, 4
	s_cbranch_scc0 .Lda_trail
	s_barrier
